# GEMM K-loops: the barrier closing each MFMA segment moved two MFMAs earlier (those two run at prio 2 after it) so the partner wave's MFMAs start without a handoff gap
# speedup vs baseline: 1.0124x; 1.0016x over previous
; #define PG8_STAGE(bufoff, gbase, voff) do { _Pragma("unroll") for (int _i = 0; _i < 2; ++_i) \
;         __builtin_amdgcn_global_load_lds((const unsigned*)((const char*)(gbase) + (voff)[_i]), (PG8_LAS unsigned*)(lds + (bufoff) + ldsw + _i * 8192), 16, 0, 0); } while (0)
; #define PG8_LDA(dst, b, h) do { _Pragma("unroll") for (int m = 0; m < 4; ++m) _Pragma("unroll") for (int k = 0; k < 2; ++k) dst[m][k] = *(const PG8_LAS bf16x8*)(lds + PG8_SA(b, h) + aoff + m * 2048 + k * 1024); } while (0)
; #define PG8_BAR __builtin_amdgcn_s_barrier()
; template <class Epi, class Sched, bool ALIGN_EPI = false, bool SP2 = false>
; __device__ __forceinline__ void gemm_phase(PG8_LAS unsigned char* lds, const Gemm g, const Sched& S, const Epi& E) {
;     ...
;         for (int t = 0; t < nt; t += 2) {
;             const bool last = (t == nt - 2);
;             const char* a1 = cA + (size_t)(t + 1) * kstep + (t >= g.kj_t ? g.kj_bytes : 0);
;             const char* a2 = last ? nA : cA + (size_t)(t + 2) * kstep + (t + 2 >= g.kj_t ? g.kj_bytes : 0); const char* b2 = last ? nB : cB + (size_t)(t + 2) * kstep;
;             const char* a3 = a2 + kstep; const char* b3 = b2 + kstep;
;             if (last && has_next) S.a_ready(nxt);
;             if constexpr (Epi::MIDK) { if (t == g.kj_t) E.midk(acc, cur, wr, fr); }
;             if constexpr (SP2) {
;             PG8_LDB(B0, 0, 0); PG8_LDB(B1, 0, 1); PG8_SCHED; PG8_LDA(At, 0, 0); PG8_STAGE(PG8_SA(1, 1), a1 + hstepA, voffA);
;             PG8_WAIT_V(8); PG8_WAIT_L(0); PG8_BAR; PG8_MMA(0, 0, At, B0); PG8_MMA(0, 1, At, B1); PG8_BAR; PG8_SCHED;
;             PG8_LDA(At, 0, 1); PG8_STAGE(PG8_SB(0, 0), b2, voffB); PG8_STAGE(PG8_SB(0, 1), b2 + hstepB, voffB); PG8_STAGE(PG8_SA(0, 0), a2, voffA);
;             PG8_WAIT_V(8); PG8_WAIT_L(0); PG8_BAR; PG8_MMA(1, 0, At, B0); PG8_MMA(1, 1, At, B1); PG8_BAR; PG8_SCHED;
;             PG8_LDB(B0, 1, 0); PG8_LDB(B1, 1, 1); PG8_SCHED; PG8_LDA(At, 1, 0); PG8_STAGE(PG8_SA(0, 1), a2 + hstepA, voffA);
;             PG8_WAIT_V(8); PG8_WAIT_L(0); PG8_BAR; PG8_MMA(0, 0, At, B0); PG8_MMA(0, 1, At, B1); PG8_BAR; PG8_SCHED;
;             PG8_LDA(At, 1, 1); PG8_STAGE(PG8_SB(1, 0), b3, voffB); PG8_STAGE(PG8_SB(1, 1), b3 + hstepB, voffB); PG8_STAGE(PG8_SA(1, 0), a3, voffA);
;             PG8_WAIT_V(8); PG8_WAIT_L(0); PG8_BAR; PG8_MMA(1, 0, At, B0); PG8_MMA(1, 1, At, B1); PG8_BAR; PG8_SCHED;
.LBB0_79:
	ds_read_b128 v[152:155], v148
	ds_read_b128 v[156:159], v148 offset:1024
	ds_read_b128 v[160:163], v148 offset:2048
	ds_read_b128 v[168:171], v148 offset:3072
	ds_read_b128 v[172:175], v149
	ds_read_b128 v[176:179], v149 offset:1024
	ds_read_b128 v[180:183], v149 offset:2048
	ds_read_b128 v[184:187], v149 offset:3072
	s_add_u32 s24, s22, 0xfff00080
	s_addc_u32 s25, s23, -1
	s_cmp_eq_u32 s64, 60
	s_cselect_b32 s27, s17, s25
	s_cselect_b32 s26, s60, s24
	s_cselect_b32 s25, s15, s63
	s_cselect_b32 s24, s61, s62
	s_add_u32 s98, s24, 0x80
	s_addc_u32 s99, s25, 0
	s_add_u32 s100, s26, 0x80
	s_addc_u32 s101, s27, 0
	s_add_i32 m0, s13, 0xc000
	ds_read_b128 v[188:191], v150
	ds_read_b128 v[192:195], v150 offset:1024
	ds_read_b128 v[196:199], v150 offset:2048
	ds_read_b128 v[200:203], v150 offset:3072
	ds_read_b128 v[204:207], v150 offset:4096
	ds_read_b128 v[208:211], v150 offset:5120
	ds_read_b128 v[212:215], v150 offset:6144
	ds_read_b128 v[216:219], v150 offset:7168
	global_load_lds_dwordx4 v138, s[22:23]
	s_add_i32 m0, s13, 0xe000
	s_nop 0
	global_load_lds_dwordx4 v140, s[22:23]
	s_waitcnt vmcnt(8)
	s_waitcnt lgkmcnt(0)
	s_barrier
	s_setprio 1
	s_waitcnt lgkmcnt(0)
	v_mfma_f32_16x16x32_bf16 v[126:129], v[152:155], v[188:191], v[126:129]
	v_mfma_f32_16x16x32_bf16 v[126:129], v[156:159], v[192:195], v[126:129]
	v_mfma_f32_16x16x32_bf16 v[122:125], v[168:171], v[192:195], v[122:125]
	v_mfma_f32_16x16x32_bf16 v[122:125], v[160:163], v[188:191], v[122:125]
	v_mfma_f32_16x16x32_bf16 v[114:117], v[160:163], v[196:199], v[114:117]
	v_mfma_f32_16x16x32_bf16 v[114:117], v[168:171], v[200:203], v[114:117]
	v_mfma_f32_16x16x32_bf16 v[118:121], v[156:159], v[200:203], v[118:121]
	v_mfma_f32_16x16x32_bf16 v[118:121], v[152:155], v[196:199], v[118:121]
	v_mfma_f32_16x16x32_bf16 v[102:105], v[152:155], v[204:207], v[102:105]
	v_mfma_f32_16x16x32_bf16 v[102:105], v[156:159], v[208:211], v[102:105]
	v_mfma_f32_16x16x32_bf16 v[98:101], v[168:171], v[208:211], v[98:101]
	v_mfma_f32_16x16x32_bf16 v[98:101], v[160:163], v[204:207], v[98:101]
	v_mfma_f32_16x16x32_bf16 v[82:85], v[160:163], v[212:215], v[82:85]
	v_mfma_f32_16x16x32_bf16 v[82:85], v[168:171], v[216:219], v[82:85]
	v_mfma_f32_16x16x32_bf16 v[86:89], v[156:159], v[216:219], v[86:89]
	v_mfma_f32_16x16x32_bf16 v[86:89], v[152:155], v[212:215], v[86:89]
	v_mfma_f32_16x16x32_bf16 v[110:113], v[172:175], v[188:191], v[110:113]
	v_mfma_f32_16x16x32_bf16 v[110:113], v[176:179], v[192:195], v[110:113]
	v_mfma_f32_16x16x32_bf16 v[106:109], v[184:187], v[192:195], v[106:109]
	v_mfma_f32_16x16x32_bf16 v[106:109], v[180:183], v[188:191], v[106:109]
	v_mfma_f32_16x16x32_bf16 v[90:93], v[180:183], v[196:199], v[90:93]
	v_mfma_f32_16x16x32_bf16 v[90:93], v[184:187], v[200:203], v[90:93]
	v_mfma_f32_16x16x32_bf16 v[94:97], v[176:179], v[200:203], v[94:97]
	v_mfma_f32_16x16x32_bf16 v[94:97], v[172:175], v[196:199], v[94:97]
	v_mfma_f32_16x16x32_bf16 v[78:81], v[172:175], v[204:207], v[78:81]
	v_mfma_f32_16x16x32_bf16 v[78:81], v[176:179], v[208:211], v[78:81]
	v_mfma_f32_16x16x32_bf16 v[74:77], v[184:187], v[208:211], v[74:77]
	v_mfma_f32_16x16x32_bf16 v[74:77], v[180:183], v[204:207], v[74:77]
	v_mfma_f32_16x16x32_bf16 v[66:69], v[180:183], v[212:215], v[66:69]
	v_mfma_f32_16x16x32_bf16 v[66:69], v[184:187], v[216:219], v[66:69]
	s_setprio 2
	s_barrier
	v_mfma_f32_16x16x32_bf16 v[70:73], v[176:179], v[216:219], v[70:73]
	v_mfma_f32_16x16x32_bf16 v[70:73], v[172:175], v[212:215], v[70:73]
	s_setprio 0
	s_add_i32 s65, s38, s3
	s_mov_b32 m0, s65
	ds_read_b128 v[188:191], v150 offset:16384
	ds_read_b128 v[192:195], v150 offset:17408
	ds_read_b128 v[196:199], v150 offset:18432
	ds_read_b128 v[200:203], v150 offset:19456
	ds_read_b128 v[204:207], v150 offset:20480
	ds_read_b128 v[208:211], v150 offset:21504
	ds_read_b128 v[212:215], v150 offset:22528
	ds_read_b128 v[216:219], v150 offset:23552
	global_load_lds_dwordx4 v134, s[24:25]
	s_add_i32 m0, s65, 0x2000
	s_add_u32 s66, s24, 0x100000
	s_addc_u32 s67, s25, 0
	s_add_i32 s65, s39, s3
	global_load_lds_dwordx4 v130, s[24:25]
	s_mov_b32 m0, s65
	s_nop 0
	global_load_lds_dwordx4 v134, s[66:67]
	s_add_i32 m0, s65, 0x2000
	s_nop 0
	global_load_lds_dwordx4 v130, s[66:67]
	s_mov_b32 m0, s13
	s_nop 0
	global_load_lds_dwordx4 v136, s[26:27]
	s_mov_b32 m0, s30
	s_nop 0
	global_load_lds_dwordx4 v132, s[26:27]
	s_waitcnt vmcnt(8)
	s_waitcnt lgkmcnt(0)
	s_barrier
	s_setprio 1
	s_waitcnt lgkmcnt(0)
	v_mfma_f32_16x16x32_bf16 v[62:65], v[152:155], v[188:191], v[62:65]
	v_mfma_f32_16x16x32_bf16 v[62:65], v[156:159], v[192:195], v[62:65]
	v_mfma_f32_16x16x32_bf16 v[58:61], v[168:171], v[192:195], v[58:61]
	v_mfma_f32_16x16x32_bf16 v[58:61], v[160:163], v[188:191], v[58:61]
	v_mfma_f32_16x16x32_bf16 v[50:53], v[160:163], v[196:199], v[50:53]
	v_mfma_f32_16x16x32_bf16 v[50:53], v[168:171], v[200:203], v[50:53]
	v_mfma_f32_16x16x32_bf16 v[54:57], v[156:159], v[200:203], v[54:57]
	v_mfma_f32_16x16x32_bf16 v[54:57], v[152:155], v[196:199], v[54:57]
	v_mfma_f32_16x16x32_bf16 v[38:41], v[152:155], v[204:207], v[38:41]
	v_mfma_f32_16x16x32_bf16 v[38:41], v[156:159], v[208:211], v[38:41]
	v_mfma_f32_16x16x32_bf16 v[34:37], v[168:171], v[208:211], v[34:37]
	v_mfma_f32_16x16x32_bf16 v[34:37], v[160:163], v[204:207], v[34:37]
	v_mfma_f32_16x16x32_bf16 v[18:21], v[160:163], v[212:215], v[18:21]
	v_mfma_f32_16x16x32_bf16 v[18:21], v[168:171], v[216:219], v[18:21]
	v_mfma_f32_16x16x32_bf16 v[22:25], v[156:159], v[216:219], v[22:25]
	v_mfma_f32_16x16x32_bf16 v[22:25], v[152:155], v[212:215], v[22:25]
	v_mfma_f32_16x16x32_bf16 v[46:49], v[172:175], v[188:191], v[46:49]
	v_mfma_f32_16x16x32_bf16 v[46:49], v[176:179], v[192:195], v[46:49]
	v_mfma_f32_16x16x32_bf16 v[42:45], v[184:187], v[192:195], v[42:45]
	v_mfma_f32_16x16x32_bf16 v[42:45], v[180:183], v[188:191], v[42:45]
	v_mfma_f32_16x16x32_bf16 v[26:29], v[180:183], v[196:199], v[26:29]
	v_mfma_f32_16x16x32_bf16 v[26:29], v[184:187], v[200:203], v[26:29]
	v_mfma_f32_16x16x32_bf16 v[30:33], v[176:179], v[200:203], v[30:33]
	v_mfma_f32_16x16x32_bf16 v[30:33], v[172:175], v[196:199], v[30:33]
	v_mfma_f32_16x16x32_bf16 v[14:17], v[172:175], v[204:207], v[14:17]
	v_mfma_f32_16x16x32_bf16 v[14:17], v[176:179], v[208:211], v[14:17]
	v_mfma_f32_16x16x32_bf16 v[10:13], v[184:187], v[208:211], v[10:13]
	v_mfma_f32_16x16x32_bf16 v[10:13], v[180:183], v[204:207], v[10:13]
	v_mfma_f32_16x16x32_bf16 v[2:5], v[180:183], v[212:215], v[2:5]
	v_mfma_f32_16x16x32_bf16 v[2:5], v[184:187], v[216:219], v[2:5]
	s_setprio 2
	s_barrier
; #define PG8_STAGE(bufoff, gbase, voff) do { _Pragma("unroll") for (int _i = 0; _i < 2; ++_i) \
;         __builtin_amdgcn_global_load_lds((const unsigned*)((const char*)(gbase) + (voff)[_i]), (PG8_LAS unsigned*)(lds + (bufoff) + ldsw + _i * 8192), 16, 0, 0); } while (0)
; #define PG8_LDA(dst, b, h) do { _Pragma("unroll") for (int m = 0; m < 4; ++m) _Pragma("unroll") for (int k = 0; k < 2; ++k) dst[m][k] = *(const PG8_LAS bf16x8*)(lds + PG8_SA(b, h) + aoff + m * 2048 + k * 1024); } while (0)
; #define PG8_LDB(dst, b, h) do { _Pragma("unroll") for (int n = 0; n < 2; ++n) _Pragma("unroll") for (int k = 0; k < 2; ++k) dst[n][k] = *(const PG8_LAS bf16x8*)(lds + PG8_SB(b, h) + boff + n * 2048 + k * 1024); } while (0)
; #define PG8_MMA(ai, bj, At, Bt) do { __builtin_amdgcn_s_setprio(1); _Pragma("unroll") for (int m = 0; m < 4; ++m) _Pragma("unroll") for (int n = 0; n < 2; ++n) _Pragma("unroll") for (int k = 0; k < 2; ++k) \
;         acc[ai][bj][m][n] = __builtin_amdgcn_mfma_f32_16x16x32_bf16(Bt[n][k], At[m][k], acc[ai][bj][m][n], 0, 0, 0); __builtin_amdgcn_s_setprio(0); } while (0)
; template <class Epi, class Sched, bool ALIGN_EPI = false, bool SP2 = false>
; __device__ __forceinline__ void gemm_phase(PG8_LAS unsigned char* lds, const Gemm g, const Sched& S, const Epi& E) {
;     ...
;             if constexpr (SP2) {
;             PG8_LDB(B0, 0, 0); PG8_LDB(B1, 0, 1); PG8_SCHED; PG8_LDA(At, 0, 0); PG8_STAGE(PG8_SA(1, 1), a1 + hstepA, voffA);
;             PG8_WAIT_V(8); PG8_WAIT_L(0); PG8_BAR; PG8_MMA(0, 0, At, B0); PG8_MMA(0, 1, At, B1); PG8_BAR; PG8_SCHED;
;             PG8_LDA(At, 0, 1); PG8_STAGE(PG8_SB(0, 0), b2, voffB); PG8_STAGE(PG8_SB(0, 1), b2 + hstepB, voffB); PG8_STAGE(PG8_SA(0, 0), a2, voffA);
;             PG8_WAIT_V(8); PG8_WAIT_L(0); PG8_BAR; PG8_MMA(1, 0, At, B0); PG8_MMA(1, 1, At, B1); PG8_BAR; PG8_SCHED;
;             PG8_LDB(B0, 1, 0); PG8_LDB(B1, 1, 1); PG8_SCHED; PG8_LDA(At, 1, 0); PG8_STAGE(PG8_SA(0, 1), a2 + hstepA, voffA);
;             PG8_WAIT_V(8); PG8_WAIT_L(0); PG8_BAR; PG8_MMA(0, 0, At, B0); PG8_MMA(0, 1, At, B1); PG8_BAR; PG8_SCHED;
;             PG8_LDA(At, 1, 1); PG8_STAGE(PG8_SB(1, 0), b3, voffB); PG8_STAGE(PG8_SB(1, 1), b3 + hstepB, voffB); PG8_STAGE(PG8_SA(1, 0), a3, voffA);
;             PG8_WAIT_V(8); PG8_WAIT_L(0); PG8_BAR; PG8_MMA(1, 0, At, B0); PG8_MMA(1, 1, At, B1); PG8_BAR; PG8_SCHED;
	v_mfma_f32_16x16x32_bf16 v[6:9], v[176:179], v[216:219], v[6:9]
	v_mfma_f32_16x16x32_bf16 v[6:9], v[172:175], v[212:215], v[6:9]
	s_setprio 0
	s_add_i32 s65, 0, 0x18000
	v_add_u32_e32 v151, s65, v146
	s_add_i32 s66, 0, 0x1c000
	ds_read_b128 v[152:155], v151
	ds_read_b128 v[156:159], v151 offset:1024
	ds_read_b128 v[160:163], v151 offset:2048
	ds_read_b128 v[168:171], v151 offset:3072
	v_add_u32_e32 v151, s66, v146
	ds_read_b128 v[172:175], v151
	ds_read_b128 v[176:179], v151 offset:1024
	ds_read_b128 v[180:183], v151 offset:2048
	ds_read_b128 v[184:187], v151 offset:3072
	s_add_u32 s26, s26, 0x100000
	s_addc_u32 s27, s27, 0
	s_mov_b32 m0, s31
	ds_read_b128 v[188:191], v150 offset:32768
	ds_read_b128 v[192:195], v150 offset:33792
	ds_read_b128 v[196:199], v150 offset:34816
	ds_read_b128 v[200:203], v150 offset:35840
	ds_read_b128 v[204:207], v150 offset:36864
	ds_read_b128 v[208:211], v150 offset:37888
	ds_read_b128 v[212:215], v150 offset:38912
	ds_read_b128 v[216:219], v150 offset:39936
	global_load_lds_dwordx4 v136, s[26:27]
	s_mov_b32 m0, s33
	s_nop 0
	global_load_lds_dwordx4 v132, s[26:27]
	s_waitcnt vmcnt(8)
	s_waitcnt lgkmcnt(0)
	s_barrier
	s_setprio 1
	s_waitcnt lgkmcnt(0)
	v_mfma_f32_16x16x32_bf16 v[126:129], v[152:155], v[188:191], v[126:129]
	v_mfma_f32_16x16x32_bf16 v[126:129], v[156:159], v[192:195], v[126:129]
	v_mfma_f32_16x16x32_bf16 v[122:125], v[168:171], v[192:195], v[122:125]
	v_mfma_f32_16x16x32_bf16 v[122:125], v[160:163], v[188:191], v[122:125]
	v_mfma_f32_16x16x32_bf16 v[114:117], v[160:163], v[196:199], v[114:117]
	v_mfma_f32_16x16x32_bf16 v[114:117], v[168:171], v[200:203], v[114:117]
	v_mfma_f32_16x16x32_bf16 v[118:121], v[156:159], v[200:203], v[118:121]
	v_mfma_f32_16x16x32_bf16 v[118:121], v[152:155], v[196:199], v[118:121]
	v_mfma_f32_16x16x32_bf16 v[102:105], v[152:155], v[204:207], v[102:105]
	v_mfma_f32_16x16x32_bf16 v[102:105], v[156:159], v[208:211], v[102:105]
	v_mfma_f32_16x16x32_bf16 v[98:101], v[168:171], v[208:211], v[98:101]
	v_mfma_f32_16x16x32_bf16 v[98:101], v[160:163], v[204:207], v[98:101]
	v_mfma_f32_16x16x32_bf16 v[82:85], v[160:163], v[212:215], v[82:85]
	v_mfma_f32_16x16x32_bf16 v[82:85], v[168:171], v[216:219], v[82:85]
	v_mfma_f32_16x16x32_bf16 v[86:89], v[156:159], v[216:219], v[86:89]
	v_mfma_f32_16x16x32_bf16 v[86:89], v[152:155], v[212:215], v[86:89]
	v_mfma_f32_16x16x32_bf16 v[110:113], v[172:175], v[188:191], v[110:113]
	v_mfma_f32_16x16x32_bf16 v[110:113], v[176:179], v[192:195], v[110:113]
	v_mfma_f32_16x16x32_bf16 v[106:109], v[184:187], v[192:195], v[106:109]
	v_mfma_f32_16x16x32_bf16 v[106:109], v[180:183], v[188:191], v[106:109]
	v_mfma_f32_16x16x32_bf16 v[90:93], v[180:183], v[196:199], v[90:93]
	v_mfma_f32_16x16x32_bf16 v[90:93], v[184:187], v[200:203], v[90:93]
	v_mfma_f32_16x16x32_bf16 v[94:97], v[176:179], v[200:203], v[94:97]
	v_mfma_f32_16x16x32_bf16 v[94:97], v[172:175], v[196:199], v[94:97]
	v_mfma_f32_16x16x32_bf16 v[78:81], v[172:175], v[204:207], v[78:81]
	v_mfma_f32_16x16x32_bf16 v[78:81], v[176:179], v[208:211], v[78:81]
	v_mfma_f32_16x16x32_bf16 v[74:77], v[184:187], v[208:211], v[74:77]
	v_mfma_f32_16x16x32_bf16 v[74:77], v[180:183], v[204:207], v[74:77]
	v_mfma_f32_16x16x32_bf16 v[66:69], v[180:183], v[212:215], v[66:69]
	v_mfma_f32_16x16x32_bf16 v[66:69], v[184:187], v[216:219], v[66:69]
	s_setprio 2
	s_barrier
	v_mfma_f32_16x16x32_bf16 v[70:73], v[176:179], v[216:219], v[70:73]
	v_mfma_f32_16x16x32_bf16 v[70:73], v[172:175], v[212:215], v[70:73]
	s_setprio 0
	s_add_i32 s26, s65, s3
	s_mov_b32 m0, s26
	ds_read_b128 v[188:191], v150 offset:49152
	ds_read_b128 v[192:195], v150 offset:50176
	ds_read_b128 v[196:199], v150 offset:51200
	ds_read_b128 v[200:203], v150 offset:52224
	ds_read_b128 v[204:207], v150 offset:53248
	ds_read_b128 v[208:211], v150 offset:54272
	ds_read_b128 v[212:215], v150 offset:55296
	ds_read_b128 v[216:219], v150 offset:56320
	global_load_lds_dwordx4 v134, s[98:99]
	s_add_i32 m0, s26, 0x2000
	s_add_u32 s24, s24, 0x100080
	s_addc_u32 s25, s25, 0
	s_add_i32 s26, s66, s3
	global_load_lds_dwordx4 v130, s[98:99]
	s_mov_b32 m0, s26
	s_nop 0
	global_load_lds_dwordx4 v134, s[24:25]
	s_add_i32 m0, s26, 0x2000
	s_nop 0
	global_load_lds_dwordx4 v130, s[24:25]
	s_mov_b32 m0, s35
	s_nop 0
	global_load_lds_dwordx4 v136, s[100:101]
	s_mov_b32 m0, s36
	s_nop 0
	global_load_lds_dwordx4 v132, s[100:101]
	s_waitcnt vmcnt(8)
	s_waitcnt lgkmcnt(0)
	s_barrier
	s_setprio 1
	s_waitcnt lgkmcnt(0)
	v_mfma_f32_16x16x32_bf16 v[62:65], v[152:155], v[188:191], v[62:65]
	v_mfma_f32_16x16x32_bf16 v[62:65], v[156:159], v[192:195], v[62:65]
	v_mfma_f32_16x16x32_bf16 v[58:61], v[168:171], v[192:195], v[58:61]
	v_mfma_f32_16x16x32_bf16 v[58:61], v[160:163], v[188:191], v[58:61]
	v_mfma_f32_16x16x32_bf16 v[50:53], v[160:163], v[196:199], v[50:53]
	v_mfma_f32_16x16x32_bf16 v[50:53], v[168:171], v[200:203], v[50:53]
	v_mfma_f32_16x16x32_bf16 v[54:57], v[156:159], v[200:203], v[54:57]
	v_mfma_f32_16x16x32_bf16 v[54:57], v[152:155], v[196:199], v[54:57]
	v_mfma_f32_16x16x32_bf16 v[38:41], v[152:155], v[204:207], v[38:41]
	v_mfma_f32_16x16x32_bf16 v[38:41], v[156:159], v[208:211], v[38:41]
	v_mfma_f32_16x16x32_bf16 v[34:37], v[168:171], v[208:211], v[34:37]
	v_mfma_f32_16x16x32_bf16 v[34:37], v[160:163], v[204:207], v[34:37]
	v_mfma_f32_16x16x32_bf16 v[18:21], v[160:163], v[212:215], v[18:21]
	v_mfma_f32_16x16x32_bf16 v[18:21], v[168:171], v[216:219], v[18:21]
	v_mfma_f32_16x16x32_bf16 v[22:25], v[156:159], v[216:219], v[22:25]
	v_mfma_f32_16x16x32_bf16 v[22:25], v[152:155], v[212:215], v[22:25]
	v_mfma_f32_16x16x32_bf16 v[46:49], v[172:175], v[188:191], v[46:49]
	v_mfma_f32_16x16x32_bf16 v[46:49], v[176:179], v[192:195], v[46:49]
	v_mfma_f32_16x16x32_bf16 v[42:45], v[184:187], v[192:195], v[42:45]
	v_mfma_f32_16x16x32_bf16 v[42:45], v[180:183], v[188:191], v[42:45]
	v_mfma_f32_16x16x32_bf16 v[26:29], v[180:183], v[196:199], v[26:29]
	v_mfma_f32_16x16x32_bf16 v[26:29], v[184:187], v[200:203], v[26:29]
	v_mfma_f32_16x16x32_bf16 v[30:33], v[176:179], v[200:203], v[30:33]
	v_mfma_f32_16x16x32_bf16 v[30:33], v[172:175], v[196:199], v[30:33]
	v_mfma_f32_16x16x32_bf16 v[14:17], v[172:175], v[204:207], v[14:17]
	v_mfma_f32_16x16x32_bf16 v[14:17], v[176:179], v[208:211], v[14:17]
	v_mfma_f32_16x16x32_bf16 v[10:13], v[184:187], v[208:211], v[10:13]
	v_mfma_f32_16x16x32_bf16 v[10:13], v[180:183], v[204:207], v[10:13]
	v_mfma_f32_16x16x32_bf16 v[2:5], v[180:183], v[212:215], v[2:5]
	v_mfma_f32_16x16x32_bf16 v[2:5], v[184:187], v[216:219], v[2:5]
	s_setprio 2
	s_barrier
	v_mfma_f32_16x16x32_bf16 v[6:9], v[176:179], v[216:219], v[6:9]
	v_mfma_f32_16x16x32_bf16 v[6:9], v[172:175], v[212:215], v[6:9]
	s_setprio 0
	s_add_i32 s64, s64, 2
	s_add_u32 s22, s22, 0x100
	s_addc_u32 s23, s23, 0
	s_add_u32 s62, s62, 0x100
	s_addc_u32 s63, s63, 0
	s_cmp_gt_u32 s64, 61
	s_cbranch_scc0 .LBB0_79
	s_and_b64 vcc, exec, s[10:11]
	s_cbranch_vccz .LBB0_82
	s_barrier

; #define PG8_STAGE(bufoff, gbase, voff) do { _Pragma("unroll") for (int _i = 0; _i < 2; ++_i) \
;         __builtin_amdgcn_global_load_lds((const unsigned*)((const char*)(gbase) + (voff)[_i]), (PG8_LAS unsigned*)(lds + (bufoff) + ldsw + _i * 8192), 16, 0, 0); } while (0)
; #define PG8_LDA(dst, b, h) do { _Pragma("unroll") for (int m = 0; m < 4; ++m) _Pragma("unroll") for (int k = 0; k < 2; ++k) dst[m][k] = *(const PG8_LAS bf16x8*)(lds + PG8_SA(b, h) + aoff + m * 2048 + k * 1024); } while (0)
; #define PG8_BAR __builtin_amdgcn_s_barrier()
; template <class Epi, class Sched, bool ALIGN_EPI = false, bool SP2 = false>
; __device__ __forceinline__ void gemm_phase(PG8_LAS unsigned char* lds, const Gemm g, const Sched& S, const Epi& E) {
;     ...
;         for (int t = 0; t < nt; t += 2) {
;             const bool last = (t == nt - 2);
;             const char* a1 = cA + (size_t)(t + 1) * kstep + (t >= g.kj_t ? g.kj_bytes : 0);
;             const char* a2 = last ? nA : cA + (size_t)(t + 2) * kstep + (t + 2 >= g.kj_t ? g.kj_bytes : 0); const char* b2 = last ? nB : cB + (size_t)(t + 2) * kstep;
;             const char* a3 = a2 + kstep; const char* b3 = b2 + kstep;
;             if (last && has_next) S.a_ready(nxt);
;             if constexpr (Epi::MIDK) { if (t == g.kj_t) E.midk(acc, cur, wr, fr); }
;             if constexpr (SP2) {
;             PG8_LDB(B0, 0, 0); PG8_LDB(B1, 0, 1); PG8_SCHED; PG8_LDA(At, 0, 0); PG8_STAGE(PG8_SA(1, 1), a1 + hstepA, voffA);
;             PG8_WAIT_V(8); PG8_WAIT_L(0); PG8_BAR; PG8_MMA(0, 0, At, B0); PG8_MMA(0, 1, At, B1); PG8_BAR; PG8_SCHED;
;             PG8_LDA(At, 0, 1); PG8_STAGE(PG8_SB(0, 0), b2, voffB); PG8_STAGE(PG8_SB(0, 1), b2 + hstepB, voffB); PG8_STAGE(PG8_SA(0, 0), a2, voffA);
;             PG8_WAIT_V(8); PG8_WAIT_L(0); PG8_BAR; PG8_MMA(1, 0, At, B0); PG8_MMA(1, 1, At, B1); PG8_BAR; PG8_SCHED;
;             PG8_LDB(B0, 1, 0); PG8_LDB(B1, 1, 1); PG8_SCHED; PG8_LDA(At, 1, 0); PG8_STAGE(PG8_SA(0, 1), a2 + hstepA, voffA);
;             PG8_WAIT_V(8); PG8_WAIT_L(0); PG8_BAR; PG8_MMA(0, 0, At, B0); PG8_MMA(0, 1, At, B1); PG8_BAR; PG8_SCHED;
;             PG8_LDA(At, 1, 1); PG8_STAGE(PG8_SB(1, 0), b3, voffB); PG8_STAGE(PG8_SB(1, 1), b3 + hstepB, voffB); PG8_STAGE(PG8_SA(1, 0), a3, voffA);
;             PG8_WAIT_V(8); PG8_WAIT_L(0); PG8_BAR; PG8_MMA(1, 0, At, B0); PG8_MMA(1, 1, At, B1); PG8_BAR; PG8_SCHED;
.LBB0_436:
	s_cmp_lt_u32 s65, 64
	s_cselect_b32 s67, 0, 0x4000
	s_add_i32 s66, s65, 2
	s_cmp_lt_u32 s65, 62
	s_cselect_b32 s30, 0, 0x4000
	s_add_u32 s30, s30, s4
	v_add_u32_e32 v3, s53, v167
	s_addc_u32 s31, 0, s5
	ds_read_b128 v[140:143], v3
	ds_read_b128 v[144:147], v3 offset:1024
	ds_read_b128 v[148:151], v3 offset:2048
	ds_read_b128 v[152:155], v3 offset:3072
	v_add_u32_e32 v3, s60, v167
	s_add_u32 s30, s28, s30
	ds_read_b128 v[156:159], v3
	ds_read_b128 v[160:163], v3 offset:1024
	ds_read_b128 v[186:189], v3 offset:2048
	ds_read_b128 v[196:199], v3 offset:3072
	s_addc_u32 s31, s29, s31
	s_add_u32 s30, s30, 0x100
	s_addc_u32 s31, s31, 0
	s_add_u32 s68, s63, s4
	s_addc_u32 s69, s64, s5
	s_cmpk_eq_i32 s4, 0x3f00
	s_cselect_b32 s35, s23, s31
	s_cselect_b32 s34, s22, s30
	s_cselect_b32 s31, s21, s69
	s_cselect_b32 s30, s62, s68
	s_add_u32 s98, s30, 0x80
	s_addc_u32 s99, s31, 0
	s_add_u32 s100, s34, 0x80
	s_addc_u32 s101, s35, 0
	s_add_u32 s68, s67, s4
	s_addc_u32 s69, 0, s5
	s_add_u32 s68, s68, s28
	s_addc_u32 s69, s69, s29
	s_add_i32 m0, s27, 0xc000
	ds_read_b128 v[200:203], v194
	ds_read_b128 v[204:207], v194 offset:1024
	ds_read_b128 v[208:211], v194 offset:2048
	ds_read_b128 v[212:215], v194 offset:3072
	ds_read_b128 v[216:219], v194 offset:4096
	ds_read_b128 v[220:223], v194 offset:5120
	ds_read_b128 v[224:227], v194 offset:6144
	ds_read_b128 v[228:231], v194 offset:7168
	global_load_lds_dwordx4 v178, s[68:69]
	s_add_i32 m0, s27, 0xe000
	s_nop 0
	global_load_lds_dwordx4 v176, s[68:69]
	s_waitcnt vmcnt(8)
	s_waitcnt lgkmcnt(0)
	s_barrier
	s_setprio 1
	s_waitcnt lgkmcnt(0)
	v_mfma_f32_16x16x32_bf16 v[130:133], v[140:143], v[200:203], v[130:133]
	v_mfma_f32_16x16x32_bf16 v[130:133], v[144:147], v[204:207], v[130:133]
	v_mfma_f32_16x16x32_bf16 v[126:129], v[152:155], v[204:207], v[126:129]
	v_mfma_f32_16x16x32_bf16 v[126:129], v[148:151], v[200:203], v[126:129]
	v_mfma_f32_16x16x32_bf16 v[110:113], v[148:151], v[208:211], v[110:113]
	v_mfma_f32_16x16x32_bf16 v[110:113], v[152:155], v[212:215], v[110:113]
	v_mfma_f32_16x16x32_bf16 v[114:117], v[144:147], v[212:215], v[114:117]
	v_mfma_f32_16x16x32_bf16 v[114:117], v[140:143], v[208:211], v[114:117]
	v_mfma_f32_16x16x32_bf16 v[98:101], v[140:143], v[216:219], v[98:101]
	v_mfma_f32_16x16x32_bf16 v[98:101], v[144:147], v[220:223], v[98:101]
	v_mfma_f32_16x16x32_bf16 v[94:97], v[152:155], v[220:223], v[94:97]
	v_mfma_f32_16x16x32_bf16 v[94:97], v[148:151], v[216:219], v[94:97]
	v_mfma_f32_16x16x32_bf16 v[78:81], v[148:151], v[224:227], v[78:81]
	v_mfma_f32_16x16x32_bf16 v[78:81], v[152:155], v[228:231], v[78:81]
	v_mfma_f32_16x16x32_bf16 v[82:85], v[144:147], v[228:231], v[82:85]
	v_mfma_f32_16x16x32_bf16 v[82:85], v[140:143], v[224:227], v[82:85]
	v_mfma_f32_16x16x32_bf16 v[122:125], v[156:159], v[200:203], v[122:125]
	v_mfma_f32_16x16x32_bf16 v[122:125], v[160:163], v[204:207], v[122:125]
	v_mfma_f32_16x16x32_bf16 v[118:121], v[196:199], v[204:207], v[118:121]
	v_mfma_f32_16x16x32_bf16 v[118:121], v[186:189], v[200:203], v[118:121]
	v_mfma_f32_16x16x32_bf16 v[102:105], v[186:189], v[208:211], v[102:105]
	v_mfma_f32_16x16x32_bf16 v[102:105], v[196:199], v[212:215], v[102:105]
	v_mfma_f32_16x16x32_bf16 v[106:109], v[160:163], v[212:215], v[106:109]
	v_mfma_f32_16x16x32_bf16 v[106:109], v[156:159], v[208:211], v[106:109]
	v_mfma_f32_16x16x32_bf16 v[90:93], v[156:159], v[216:219], v[90:93]
	v_mfma_f32_16x16x32_bf16 v[90:93], v[160:163], v[220:223], v[90:93]
	v_mfma_f32_16x16x32_bf16 v[86:89], v[196:199], v[220:223], v[86:89]
	v_mfma_f32_16x16x32_bf16 v[86:89], v[186:189], v[216:219], v[86:89]
	v_mfma_f32_16x16x32_bf16 v[70:73], v[186:189], v[224:227], v[70:73]
	v_mfma_f32_16x16x32_bf16 v[70:73], v[196:199], v[228:231], v[70:73]
	s_setprio 2
	s_barrier
	v_mfma_f32_16x16x32_bf16 v[74:77], v[160:163], v[228:231], v[74:77]
	v_mfma_f32_16x16x32_bf16 v[74:77], v[156:159], v[224:227], v[74:77]
	s_setprio 0
	s_add_i32 s67, s53, s36
	s_mov_b32 m0, s67
	ds_read_b128 v[200:203], v194 offset:16384
	ds_read_b128 v[204:207], v194 offset:17408
	ds_read_b128 v[208:211], v194 offset:18432
	ds_read_b128 v[212:215], v194 offset:19456
	ds_read_b128 v[216:219], v194 offset:20480
	ds_read_b128 v[220:223], v194 offset:21504
	ds_read_b128 v[224:227], v194 offset:22528
	ds_read_b128 v[228:231], v194 offset:23552
	global_load_lds_dwordx4 v170, s[30:31]
	s_add_i32 m0, s67, 0x2000
	s_add_u32 s68, s30, 0x200000
	s_addc_u32 s69, s31, 0
	s_add_i32 s67, s60, s36
	global_load_lds_dwordx4 v174, s[30:31]
	s_mov_b32 m0, s67
	s_nop 0
	global_load_lds_dwordx4 v170, s[68:69]
	s_add_i32 m0, s67, 0x2000
	s_nop 0
	global_load_lds_dwordx4 v174, s[68:69]
	s_mov_b32 m0, s27
	s_nop 0
	global_load_lds_dwordx4 v168, s[34:35]
	s_mov_b32 m0, s37
	s_nop 0
	global_load_lds_dwordx4 v172, s[34:35]
	s_waitcnt vmcnt(8)
	s_waitcnt lgkmcnt(0)
	s_barrier
; #define PG8_STAGE(bufoff, gbase, voff) do { _Pragma("unroll") for (int _i = 0; _i < 2; ++_i) \
;         __builtin_amdgcn_global_load_lds((const unsigned*)((const char*)(gbase) + (voff)[_i]), (PG8_LAS unsigned*)(lds + (bufoff) + ldsw + _i * 8192), 16, 0, 0); } while (0)
; #define PG8_LDA(dst, b, h) do { _Pragma("unroll") for (int m = 0; m < 4; ++m) _Pragma("unroll") for (int k = 0; k < 2; ++k) dst[m][k] = *(const PG8_LAS bf16x8*)(lds + PG8_SA(b, h) + aoff + m * 2048 + k * 1024); } while (0)
; #define PG8_LDB(dst, b, h) do { _Pragma("unroll") for (int n = 0; n < 2; ++n) _Pragma("unroll") for (int k = 0; k < 2; ++k) dst[n][k] = *(const PG8_LAS bf16x8*)(lds + PG8_SB(b, h) + boff + n * 2048 + k * 1024); } while (0)
; #define PG8_MMA(ai, bj, At, Bt) do { __builtin_amdgcn_s_setprio(1); _Pragma("unroll") for (int m = 0; m < 4; ++m) _Pragma("unroll") for (int n = 0; n < 2; ++n) _Pragma("unroll") for (int k = 0; k < 2; ++k) \
;         acc[ai][bj][m][n] = __builtin_amdgcn_mfma_f32_16x16x32_bf16(Bt[n][k], At[m][k], acc[ai][bj][m][n], 0, 0, 0); __builtin_amdgcn_s_setprio(0); } while (0)
; template <class Epi, class Sched, bool ALIGN_EPI = false, bool SP2 = false>
; __device__ __forceinline__ void gemm_phase(PG8_LAS unsigned char* lds, const Gemm g, const Sched& S, const Epi& E) {
;     ...
;             if constexpr (SP2) {
;             PG8_LDB(B0, 0, 0); PG8_LDB(B1, 0, 1); PG8_SCHED; PG8_LDA(At, 0, 0); PG8_STAGE(PG8_SA(1, 1), a1 + hstepA, voffA);
;             PG8_WAIT_V(8); PG8_WAIT_L(0); PG8_BAR; PG8_MMA(0, 0, At, B0); PG8_MMA(0, 1, At, B1); PG8_BAR; PG8_SCHED;
;             PG8_LDA(At, 0, 1); PG8_STAGE(PG8_SB(0, 0), b2, voffB); PG8_STAGE(PG8_SB(0, 1), b2 + hstepB, voffB); PG8_STAGE(PG8_SA(0, 0), a2, voffA);
;             PG8_WAIT_V(8); PG8_WAIT_L(0); PG8_BAR; PG8_MMA(1, 0, At, B0); PG8_MMA(1, 1, At, B1); PG8_BAR; PG8_SCHED;
;             PG8_LDB(B0, 1, 0); PG8_LDB(B1, 1, 1); PG8_SCHED; PG8_LDA(At, 1, 0); PG8_STAGE(PG8_SA(0, 1), a2 + hstepA, voffA);
;             PG8_WAIT_V(8); PG8_WAIT_L(0); PG8_BAR; PG8_MMA(0, 0, At, B0); PG8_MMA(0, 1, At, B1); PG8_BAR; PG8_SCHED;
;             PG8_LDA(At, 1, 1); PG8_STAGE(PG8_SB(1, 0), b3, voffB); PG8_STAGE(PG8_SB(1, 1), b3 + hstepB, voffB); PG8_STAGE(PG8_SA(1, 0), a3, voffA);
;             PG8_WAIT_V(8); PG8_WAIT_L(0); PG8_BAR; PG8_MMA(1, 0, At, B0); PG8_MMA(1, 1, At, B1); PG8_BAR; PG8_SCHED;
	s_setprio 1
	s_waitcnt lgkmcnt(0)
	v_mfma_f32_16x16x32_bf16 v[66:69], v[140:143], v[200:203], v[66:69]
	v_mfma_f32_16x16x32_bf16 v[66:69], v[144:147], v[204:207], v[66:69]
	v_mfma_f32_16x16x32_bf16 v[62:65], v[152:155], v[204:207], v[62:65]
	v_mfma_f32_16x16x32_bf16 v[62:65], v[148:151], v[200:203], v[62:65]
	v_mfma_f32_16x16x32_bf16 v[46:49], v[148:151], v[208:211], v[46:49]
	v_mfma_f32_16x16x32_bf16 v[46:49], v[152:155], v[212:215], v[46:49]
	v_mfma_f32_16x16x32_bf16 v[50:53], v[144:147], v[212:215], v[50:53]
	v_mfma_f32_16x16x32_bf16 v[50:53], v[140:143], v[208:211], v[50:53]
	v_mfma_f32_16x16x32_bf16 v[34:37], v[140:143], v[216:219], v[34:37]
	v_mfma_f32_16x16x32_bf16 v[34:37], v[144:147], v[220:223], v[34:37]
	v_mfma_f32_16x16x32_bf16 v[30:33], v[152:155], v[220:223], v[30:33]
	v_mfma_f32_16x16x32_bf16 v[30:33], v[148:151], v[216:219], v[30:33]
	v_mfma_f32_16x16x32_bf16 v[14:17], v[148:151], v[224:227], v[14:17]
	v_mfma_f32_16x16x32_bf16 v[14:17], v[152:155], v[228:231], v[14:17]
	v_mfma_f32_16x16x32_bf16 v[18:21], v[144:147], v[228:231], v[18:21]
	v_mfma_f32_16x16x32_bf16 v[18:21], v[140:143], v[224:227], v[18:21]
	v_mfma_f32_16x16x32_bf16 v[58:61], v[156:159], v[200:203], v[58:61]
	v_mfma_f32_16x16x32_bf16 v[58:61], v[160:163], v[204:207], v[58:61]
	v_mfma_f32_16x16x32_bf16 v[54:57], v[196:199], v[204:207], v[54:57]
	v_mfma_f32_16x16x32_bf16 v[54:57], v[186:189], v[200:203], v[54:57]
	v_mfma_f32_16x16x32_bf16 v[38:41], v[186:189], v[208:211], v[38:41]
	v_mfma_f32_16x16x32_bf16 v[38:41], v[196:199], v[212:215], v[38:41]
	v_mfma_f32_16x16x32_bf16 v[42:45], v[160:163], v[212:215], v[42:45]
	v_mfma_f32_16x16x32_bf16 v[42:45], v[156:159], v[208:211], v[42:45]
	v_mfma_f32_16x16x32_bf16 v[26:29], v[156:159], v[216:219], v[26:29]
	v_mfma_f32_16x16x32_bf16 v[26:29], v[160:163], v[220:223], v[26:29]
	v_mfma_f32_16x16x32_bf16 v[22:25], v[196:199], v[220:223], v[22:25]
	v_mfma_f32_16x16x32_bf16 v[22:25], v[186:189], v[216:219], v[22:25]
	v_mfma_f32_16x16x32_bf16 v[4:7], v[186:189], v[224:227], v[6:9]
	v_mfma_f32_16x16x32_bf16 v[4:7], v[196:199], v[228:231], v[4:7]
	s_setprio 2
	s_barrier
	v_mfma_f32_16x16x32_bf16 v[10:13], v[160:163], v[228:231], v[10:13]
	v_mfma_f32_16x16x32_bf16 v[10:13], v[156:159], v[224:227], v[10:13]
	s_setprio 0
	s_add_i32 s67, 0, 0x18000
	v_add_u32_e32 v3, s67, v167
	s_add_i32 s68, 0, 0x1c000
	ds_read_b128 v[140:143], v3
	ds_read_b128 v[144:147], v3 offset:1024
	ds_read_b128 v[148:151], v3 offset:2048
	ds_read_b128 v[152:155], v3 offset:3072
	v_add_u32_e32 v3, s68, v167
	ds_read_b128 v[156:159], v3
	ds_read_b128 v[160:163], v3 offset:1024
	ds_read_b128 v[186:189], v3 offset:2048
	ds_read_b128 v[196:199], v3 offset:3072
	s_add_u32 s34, s34, 0x600000
	s_addc_u32 s35, s35, 0
	s_mov_b32 m0, s38
	ds_read_b128 v[200:203], v194 offset:32768
	ds_read_b128 v[204:207], v194 offset:33792
	ds_read_b128 v[208:211], v194 offset:34816
	ds_read_b128 v[212:215], v194 offset:35840
	ds_read_b128 v[216:219], v194 offset:36864
	ds_read_b128 v[220:223], v194 offset:37888
	ds_read_b128 v[224:227], v194 offset:38912
	ds_read_b128 v[228:231], v194 offset:39936
	global_load_lds_dwordx4 v168, s[34:35]
	s_mov_b32 m0, s39
	s_nop 0
	global_load_lds_dwordx4 v172, s[34:35]
	s_waitcnt vmcnt(8)
	s_waitcnt lgkmcnt(0)
	s_barrier
	s_setprio 1
	s_waitcnt lgkmcnt(0)
	v_mfma_f32_16x16x32_bf16 v[130:133], v[140:143], v[200:203], v[130:133]
	v_mfma_f32_16x16x32_bf16 v[130:133], v[144:147], v[204:207], v[130:133]
	v_mfma_f32_16x16x32_bf16 v[126:129], v[152:155], v[204:207], v[126:129]
	v_mfma_f32_16x16x32_bf16 v[126:129], v[148:151], v[200:203], v[126:129]
	v_mfma_f32_16x16x32_bf16 v[110:113], v[148:151], v[208:211], v[110:113]
	v_mfma_f32_16x16x32_bf16 v[110:113], v[152:155], v[212:215], v[110:113]
	v_mfma_f32_16x16x32_bf16 v[114:117], v[144:147], v[212:215], v[114:117]
	v_mfma_f32_16x16x32_bf16 v[114:117], v[140:143], v[208:211], v[114:117]
	v_mfma_f32_16x16x32_bf16 v[98:101], v[140:143], v[216:219], v[98:101]
	v_mfma_f32_16x16x32_bf16 v[98:101], v[144:147], v[220:223], v[98:101]
	v_mfma_f32_16x16x32_bf16 v[94:97], v[152:155], v[220:223], v[94:97]
	v_mfma_f32_16x16x32_bf16 v[94:97], v[148:151], v[216:219], v[94:97]
	v_mfma_f32_16x16x32_bf16 v[78:81], v[148:151], v[224:227], v[78:81]
	v_mfma_f32_16x16x32_bf16 v[78:81], v[152:155], v[228:231], v[78:81]
	v_mfma_f32_16x16x32_bf16 v[82:85], v[144:147], v[228:231], v[82:85]
	v_mfma_f32_16x16x32_bf16 v[82:85], v[140:143], v[224:227], v[82:85]
	v_mfma_f32_16x16x32_bf16 v[122:125], v[156:159], v[200:203], v[122:125]
	v_mfma_f32_16x16x32_bf16 v[122:125], v[160:163], v[204:207], v[122:125]
	v_mfma_f32_16x16x32_bf16 v[118:121], v[196:199], v[204:207], v[118:121]
	v_mfma_f32_16x16x32_bf16 v[118:121], v[186:189], v[200:203], v[118:121]
	v_mfma_f32_16x16x32_bf16 v[102:105], v[186:189], v[208:211], v[102:105]
	v_mfma_f32_16x16x32_bf16 v[102:105], v[196:199], v[212:215], v[102:105]
	v_mfma_f32_16x16x32_bf16 v[106:109], v[160:163], v[212:215], v[106:109]
	v_mfma_f32_16x16x32_bf16 v[106:109], v[156:159], v[208:211], v[106:109]
	v_mfma_f32_16x16x32_bf16 v[90:93], v[156:159], v[216:219], v[90:93]
	v_mfma_f32_16x16x32_bf16 v[90:93], v[160:163], v[220:223], v[90:93]
	v_mfma_f32_16x16x32_bf16 v[86:89], v[196:199], v[220:223], v[86:89]
	v_mfma_f32_16x16x32_bf16 v[86:89], v[186:189], v[216:219], v[86:89]
	v_mfma_f32_16x16x32_bf16 v[70:73], v[186:189], v[224:227], v[70:73]
	v_mfma_f32_16x16x32_bf16 v[70:73], v[196:199], v[228:231], v[70:73]
	s_setprio 2
	s_barrier
; #define PG8_STAGE(bufoff, gbase, voff) do { _Pragma("unroll") for (int _i = 0; _i < 2; ++_i) \
;         __builtin_amdgcn_global_load_lds((const unsigned*)((const char*)(gbase) + (voff)[_i]), (PG8_LAS unsigned*)(lds + (bufoff) + ldsw + _i * 8192), 16, 0, 0); } while (0)
; #define PG8_LDA(dst, b, h) do { _Pragma("unroll") for (int m = 0; m < 4; ++m) _Pragma("unroll") for (int k = 0; k < 2; ++k) dst[m][k] = *(const PG8_LAS bf16x8*)(lds + PG8_SA(b, h) + aoff + m * 2048 + k * 1024); } while (0)
; #define PG8_LDB(dst, b, h) do { _Pragma("unroll") for (int n = 0; n < 2; ++n) _Pragma("unroll") for (int k = 0; k < 2; ++k) dst[n][k] = *(const PG8_LAS bf16x8*)(lds + PG8_SB(b, h) + boff + n * 2048 + k * 1024); } while (0)
; #define PG8_MMA(ai, bj, At, Bt) do { __builtin_amdgcn_s_setprio(1); _Pragma("unroll") for (int m = 0; m < 4; ++m) _Pragma("unroll") for (int n = 0; n < 2; ++n) _Pragma("unroll") for (int k = 0; k < 2; ++k) \
;         acc[ai][bj][m][n] = __builtin_amdgcn_mfma_f32_16x16x32_bf16(Bt[n][k], At[m][k], acc[ai][bj][m][n], 0, 0, 0); __builtin_amdgcn_s_setprio(0); } while (0)
; template <class Epi, class Sched, bool ALIGN_EPI = false, bool SP2 = false>
; __device__ __forceinline__ void gemm_phase(PG8_LAS unsigned char* lds, const Gemm g, const Sched& S, const Epi& E) {
;     ...
;             if constexpr (SP2) {
;             PG8_LDB(B0, 0, 0); PG8_LDB(B1, 0, 1); PG8_SCHED; PG8_LDA(At, 0, 0); PG8_STAGE(PG8_SA(1, 1), a1 + hstepA, voffA);
;             PG8_WAIT_V(8); PG8_WAIT_L(0); PG8_BAR; PG8_MMA(0, 0, At, B0); PG8_MMA(0, 1, At, B1); PG8_BAR; PG8_SCHED;
;             PG8_LDA(At, 0, 1); PG8_STAGE(PG8_SB(0, 0), b2, voffB); PG8_STAGE(PG8_SB(0, 1), b2 + hstepB, voffB); PG8_STAGE(PG8_SA(0, 0), a2, voffA);
;             PG8_WAIT_V(8); PG8_WAIT_L(0); PG8_BAR; PG8_MMA(1, 0, At, B0); PG8_MMA(1, 1, At, B1); PG8_BAR; PG8_SCHED;
;             PG8_LDB(B0, 1, 0); PG8_LDB(B1, 1, 1); PG8_SCHED; PG8_LDA(At, 1, 0); PG8_STAGE(PG8_SA(0, 1), a2 + hstepA, voffA);
;             PG8_WAIT_V(8); PG8_WAIT_L(0); PG8_BAR; PG8_MMA(0, 0, At, B0); PG8_MMA(0, 1, At, B1); PG8_BAR; PG8_SCHED;
;             PG8_LDA(At, 1, 1); PG8_STAGE(PG8_SB(1, 0), b3, voffB); PG8_STAGE(PG8_SB(1, 1), b3 + hstepB, voffB); PG8_STAGE(PG8_SA(1, 0), a3, voffA);
;             PG8_WAIT_V(8); PG8_WAIT_L(0); PG8_BAR; PG8_MMA(1, 0, At, B0); PG8_MMA(1, 1, At, B1); PG8_BAR; PG8_SCHED;
	v_mfma_f32_16x16x32_bf16 v[74:77], v[160:163], v[228:231], v[74:77]
	v_mfma_f32_16x16x32_bf16 v[74:77], v[156:159], v[224:227], v[74:77]
	s_setprio 0
	s_add_i32 s34, s67, s36
	s_mov_b32 m0, s34
	ds_read_b128 v[200:203], v194 offset:49152
	ds_read_b128 v[204:207], v194 offset:50176
	ds_read_b128 v[208:211], v194 offset:51200
	ds_read_b128 v[212:215], v194 offset:52224
	ds_read_b128 v[216:219], v194 offset:53248
	ds_read_b128 v[220:223], v194 offset:54272
	ds_read_b128 v[224:227], v194 offset:55296
	ds_read_b128 v[228:231], v194 offset:56320
	global_load_lds_dwordx4 v170, s[98:99]
	s_add_i32 m0, s34, 0x2000
	s_add_u32 s30, s30, 0x200080
	s_addc_u32 s31, s31, 0
	s_add_i32 s34, s68, s36
	global_load_lds_dwordx4 v174, s[98:99]
	s_mov_b32 m0, s34
	s_nop 0
	global_load_lds_dwordx4 v170, s[30:31]
	s_add_i32 m0, s34, 0x2000
	s_nop 0
	global_load_lds_dwordx4 v174, s[30:31]
	s_mov_b32 m0, s41
	s_nop 0
	global_load_lds_dwordx4 v168, s[100:101]
	s_mov_b32 m0, s50
	s_nop 0
	global_load_lds_dwordx4 v172, s[100:101]
	s_waitcnt vmcnt(8)
	s_waitcnt lgkmcnt(0)
	s_barrier
	s_setprio 1
	s_waitcnt lgkmcnt(0)
	v_mfma_f32_16x16x32_bf16 v[66:69], v[140:143], v[200:203], v[66:69]
	v_mfma_f32_16x16x32_bf16 v[66:69], v[144:147], v[204:207], v[66:69]
	v_mfma_f32_16x16x32_bf16 v[62:65], v[152:155], v[204:207], v[62:65]
	v_mfma_f32_16x16x32_bf16 v[62:65], v[148:151], v[200:203], v[62:65]
	v_mfma_f32_16x16x32_bf16 v[46:49], v[148:151], v[208:211], v[46:49]
	v_mfma_f32_16x16x32_bf16 v[46:49], v[152:155], v[212:215], v[46:49]
	v_mfma_f32_16x16x32_bf16 v[50:53], v[144:147], v[212:215], v[50:53]
	v_mfma_f32_16x16x32_bf16 v[50:53], v[140:143], v[208:211], v[50:53]
	v_mfma_f32_16x16x32_bf16 v[34:37], v[140:143], v[216:219], v[34:37]
	v_mfma_f32_16x16x32_bf16 v[34:37], v[144:147], v[220:223], v[34:37]
	v_mfma_f32_16x16x32_bf16 v[30:33], v[152:155], v[220:223], v[30:33]
	v_mfma_f32_16x16x32_bf16 v[30:33], v[148:151], v[216:219], v[30:33]
	v_mfma_f32_16x16x32_bf16 v[14:17], v[148:151], v[224:227], v[14:17]
	v_mfma_f32_16x16x32_bf16 v[14:17], v[152:155], v[228:231], v[14:17]
	v_mfma_f32_16x16x32_bf16 v[18:21], v[144:147], v[228:231], v[18:21]
	v_mfma_f32_16x16x32_bf16 v[18:21], v[140:143], v[224:227], v[18:21]
	v_mfma_f32_16x16x32_bf16 v[58:61], v[156:159], v[200:203], v[58:61]
	v_mfma_f32_16x16x32_bf16 v[58:61], v[160:163], v[204:207], v[58:61]
	v_mfma_f32_16x16x32_bf16 v[54:57], v[196:199], v[204:207], v[54:57]
	v_mfma_f32_16x16x32_bf16 v[54:57], v[186:189], v[200:203], v[54:57]
	v_mfma_f32_16x16x32_bf16 v[38:41], v[186:189], v[208:211], v[38:41]
	v_mfma_f32_16x16x32_bf16 v[38:41], v[196:199], v[212:215], v[38:41]
	v_mfma_f32_16x16x32_bf16 v[42:45], v[160:163], v[212:215], v[42:45]
	v_mfma_f32_16x16x32_bf16 v[42:45], v[156:159], v[208:211], v[42:45]
	v_mfma_f32_16x16x32_bf16 v[26:29], v[156:159], v[216:219], v[26:29]
	v_mfma_f32_16x16x32_bf16 v[26:29], v[160:163], v[220:223], v[26:29]
	v_mfma_f32_16x16x32_bf16 v[22:25], v[196:199], v[220:223], v[22:25]
	v_mfma_f32_16x16x32_bf16 v[22:25], v[186:189], v[216:219], v[22:25]
	v_mfma_f32_16x16x32_bf16 v[8:11], v[156:159], v[224:227], v[10:13]
	v_mfma_f32_16x16x32_bf16 v[10:13], v[160:163], v[228:231], v[8:11]
	s_setprio 2
	s_barrier
	v_mfma_f32_16x16x32_bf16 v[4:7], v[186:189], v[224:227], v[4:7]
	v_mfma_f32_16x16x32_bf16 v[6:9], v[196:199], v[228:231], v[4:7]
	s_setprio 0
	s_add_u32 s4, s4, 0x100
	s_addc_u32 s5, 0, s5
	s_cmpk_gt_u32 s65, 0x7d
	s_cbranch_scc0 .LBB0_434
	s_and_b64 vcc, exec, s[16:17]
	s_cbranch_vccz .LBB0_439
	s_barrier

; #define PG8_STAGE(bufoff, gbase, voff) do { _Pragma("unroll") for (int _i = 0; _i < 2; ++_i) \
;         __builtin_amdgcn_global_load_lds((const unsigned*)((const char*)(gbase) + (voff)[_i]), (PG8_LAS unsigned*)(lds + (bufoff) + ldsw + _i * 8192), 16, 0, 0); } while (0)
; #define PG8_LDA(dst, b, h) do { _Pragma("unroll") for (int m = 0; m < 4; ++m) _Pragma("unroll") for (int k = 0; k < 2; ++k) dst[m][k] = *(const PG8_LAS bf16x8*)(lds + PG8_SA(b, h) + aoff + m * 2048 + k * 1024); } while (0)
; #define PG8_BAR __builtin_amdgcn_s_barrier()
; template <class Epi, class Sched, bool ALIGN_EPI = false, bool SP2 = false>
; __device__ __forceinline__ void gemm_phase(PG8_LAS unsigned char* lds, const Gemm g, const Sched& S, const Epi& E) {
;     ...
;         for (int t = 0; t < nt; t += 2) {
;             const bool last = (t == nt - 2);
;             const char* a1 = cA + (size_t)(t + 1) * kstep + (t >= g.kj_t ? g.kj_bytes : 0);
;             const char* a2 = last ? nA : cA + (size_t)(t + 2) * kstep + (t + 2 >= g.kj_t ? g.kj_bytes : 0); const char* b2 = last ? nB : cB + (size_t)(t + 2) * kstep;
;             const char* a3 = a2 + kstep; const char* b3 = b2 + kstep;
;             if (last && has_next) S.a_ready(nxt);
;             if constexpr (Epi::MIDK) { if (t == g.kj_t) E.midk(acc, cur, wr, fr); }
;             if constexpr (SP2) {
;             PG8_LDB(B0, 0, 0); PG8_LDB(B1, 0, 1); PG8_SCHED; PG8_LDA(At, 0, 0); PG8_STAGE(PG8_SA(1, 1), a1 + hstepA, voffA);
;             PG8_WAIT_V(8); PG8_WAIT_L(0); PG8_BAR; PG8_MMA(0, 0, At, B0); PG8_MMA(0, 1, At, B1); PG8_BAR; PG8_SCHED;
;             PG8_LDA(At, 0, 1); PG8_STAGE(PG8_SB(0, 0), b2, voffB); PG8_STAGE(PG8_SB(0, 1), b2 + hstepB, voffB); PG8_STAGE(PG8_SA(0, 0), a2, voffA);
;             PG8_WAIT_V(8); PG8_WAIT_L(0); PG8_BAR; PG8_MMA(1, 0, At, B0); PG8_MMA(1, 1, At, B1); PG8_BAR; PG8_SCHED;
;             PG8_LDB(B0, 1, 0); PG8_LDB(B1, 1, 1); PG8_SCHED; PG8_LDA(At, 1, 0); PG8_STAGE(PG8_SA(0, 1), a2 + hstepA, voffA);
;             PG8_WAIT_V(8); PG8_WAIT_L(0); PG8_BAR; PG8_MMA(0, 0, At, B0); PG8_MMA(0, 1, At, B1); PG8_BAR; PG8_SCHED;
;             PG8_LDA(At, 1, 1); PG8_STAGE(PG8_SB(1, 0), b3, voffB); PG8_STAGE(PG8_SB(1, 1), b3 + hstepB, voffB); PG8_STAGE(PG8_SA(1, 0), a3, voffA);
;             PG8_WAIT_V(8); PG8_WAIT_L(0); PG8_BAR; PG8_MMA(1, 0, At, B0); PG8_MMA(1, 1, At, B1); PG8_BAR; PG8_SCHED;
.LBB0_525:
	ds_read_b128 v[146:149], v160
	ds_read_b128 v[168:171], v160 offset:1024
	ds_read_b128 v[172:175], v160 offset:2048
	ds_read_b128 v[176:179], v160 offset:3072
	ds_read_b128 v[180:183], v161
	ds_read_b128 v[184:187], v161 offset:1024
	ds_read_b128 v[188:191], v161 offset:2048
	ds_read_b128 v[192:195], v161 offset:3072
	s_add_u32 s24, s22, 0xfff00080
	s_addc_u32 s25, s23, -1
	s_cmp_eq_u32 s60, 60
	s_cselect_b32 s27, s15, s25
	s_cselect_b32 s26, s50, s24
	s_cselect_b32 s25, s13, s53
	s_cselect_b32 s24, s51, s52
	s_add_u32 s98, s24, 0x80
	s_addc_u32 s99, s25, 0
	s_add_u32 s100, s26, 0x80
	s_addc_u32 s101, s27, 0
	s_add_i32 m0, s21, 0xc000
	ds_read_b128 v[196:199], v162
	ds_read_b128 v[200:203], v162 offset:1024
	ds_read_b128 v[204:207], v162 offset:2048
	ds_read_b128 v[208:211], v162 offset:3072
	ds_read_b128 v[212:215], v162 offset:4096
	ds_read_b128 v[216:219], v162 offset:5120
	ds_read_b128 v[220:223], v162 offset:6144
	ds_read_b128 v[224:227], v162 offset:7168
	global_load_lds_dwordx4 v138, s[22:23]
	s_add_i32 m0, s21, 0xe000
	s_nop 0
	global_load_lds_dwordx4 v140, s[22:23]
	s_waitcnt vmcnt(8)
	s_waitcnt lgkmcnt(0)
	s_barrier
	s_setprio 1
	s_waitcnt lgkmcnt(0)
	v_mfma_f32_16x16x32_bf16 v[126:129], v[146:149], v[196:199], v[126:129]
	v_mfma_f32_16x16x32_bf16 v[126:129], v[168:171], v[200:203], v[126:129]
	v_mfma_f32_16x16x32_bf16 v[122:125], v[176:179], v[200:203], v[122:125]
	v_mfma_f32_16x16x32_bf16 v[122:125], v[172:175], v[196:199], v[122:125]
	v_mfma_f32_16x16x32_bf16 v[114:117], v[172:175], v[204:207], v[114:117]
	v_mfma_f32_16x16x32_bf16 v[114:117], v[176:179], v[208:211], v[114:117]
	v_mfma_f32_16x16x32_bf16 v[118:121], v[168:171], v[208:211], v[118:121]
	v_mfma_f32_16x16x32_bf16 v[118:121], v[146:149], v[204:207], v[118:121]
	v_mfma_f32_16x16x32_bf16 v[110:113], v[146:149], v[212:215], v[110:113]
	v_mfma_f32_16x16x32_bf16 v[110:113], v[168:171], v[216:219], v[110:113]
	v_mfma_f32_16x16x32_bf16 v[98:101], v[176:179], v[216:219], v[98:101]
	v_mfma_f32_16x16x32_bf16 v[98:101], v[172:175], v[212:215], v[98:101]
	v_mfma_f32_16x16x32_bf16 v[78:81], v[172:175], v[220:223], v[78:81]
	v_mfma_f32_16x16x32_bf16 v[78:81], v[176:179], v[224:227], v[78:81]
	v_mfma_f32_16x16x32_bf16 v[82:85], v[168:171], v[224:227], v[82:85]
	v_mfma_f32_16x16x32_bf16 v[82:85], v[146:149], v[220:223], v[82:85]
	v_mfma_f32_16x16x32_bf16 v[106:109], v[180:183], v[196:199], v[106:109]
	v_mfma_f32_16x16x32_bf16 v[106:109], v[184:187], v[200:203], v[106:109]
	v_mfma_f32_16x16x32_bf16 v[102:105], v[192:195], v[200:203], v[102:105]
	v_mfma_f32_16x16x32_bf16 v[102:105], v[188:191], v[196:199], v[102:105]
	v_mfma_f32_16x16x32_bf16 v[90:93], v[188:191], v[204:207], v[90:93]
	v_mfma_f32_16x16x32_bf16 v[90:93], v[192:195], v[208:211], v[90:93]
	v_mfma_f32_16x16x32_bf16 v[94:97], v[184:187], v[208:211], v[94:97]
	v_mfma_f32_16x16x32_bf16 v[94:97], v[180:183], v[204:207], v[94:97]
	v_mfma_f32_16x16x32_bf16 v[86:89], v[180:183], v[212:215], v[86:89]
	v_mfma_f32_16x16x32_bf16 v[86:89], v[184:187], v[216:219], v[86:89]
	v_mfma_f32_16x16x32_bf16 v[74:77], v[192:195], v[216:219], v[74:77]
	v_mfma_f32_16x16x32_bf16 v[74:77], v[188:191], v[212:215], v[74:77]
	v_mfma_f32_16x16x32_bf16 v[66:69], v[188:191], v[220:223], v[66:69]
	v_mfma_f32_16x16x32_bf16 v[66:69], v[192:195], v[224:227], v[66:69]
	s_setprio 2
	s_barrier
	v_mfma_f32_16x16x32_bf16 v[70:73], v[184:187], v[224:227], v[70:73]
	v_mfma_f32_16x16x32_bf16 v[70:73], v[180:183], v[220:223], v[70:73]
	s_setprio 0
	s_add_i32 s61, s38, s3
	s_mov_b32 m0, s61
	ds_read_b128 v[196:199], v162 offset:16384
	ds_read_b128 v[200:203], v162 offset:17408
	ds_read_b128 v[204:207], v162 offset:18432
	ds_read_b128 v[208:211], v162 offset:19456
	ds_read_b128 v[212:215], v162 offset:20480
	ds_read_b128 v[216:219], v162 offset:21504
	ds_read_b128 v[220:223], v162 offset:22528
	ds_read_b128 v[224:227], v162 offset:23552
	global_load_lds_dwordx4 v136, s[24:25]
	s_add_i32 m0, s61, 0x2000
	s_add_u32 s62, s24, 0x100000
	s_addc_u32 s63, s25, 0
	s_add_i32 s61, s39, s3
	global_load_lds_dwordx4 v134, s[24:25]
	s_mov_b32 m0, s61
	s_nop 0
	global_load_lds_dwordx4 v136, s[62:63]
	s_add_i32 m0, s61, 0x2000
	s_nop 0
	global_load_lds_dwordx4 v134, s[62:63]
	s_mov_b32 m0, s21
	s_nop 0
	global_load_lds_dwordx4 v130, s[26:27]
	s_mov_b32 m0, s30
	s_nop 0
	global_load_lds_dwordx4 v132, s[26:27]
	s_waitcnt vmcnt(8)
	s_waitcnt lgkmcnt(0)
	s_barrier
	s_setprio 1
	s_waitcnt lgkmcnt(0)
	v_mfma_f32_16x16x32_bf16 v[62:65], v[146:149], v[196:199], v[62:65]
	v_mfma_f32_16x16x32_bf16 v[62:65], v[168:171], v[200:203], v[62:65]
	v_mfma_f32_16x16x32_bf16 v[58:61], v[176:179], v[200:203], v[58:61]
	v_mfma_f32_16x16x32_bf16 v[58:61], v[172:175], v[196:199], v[58:61]
	v_mfma_f32_16x16x32_bf16 v[46:49], v[172:175], v[204:207], v[46:49]
	v_mfma_f32_16x16x32_bf16 v[46:49], v[176:179], v[208:211], v[46:49]
	v_mfma_f32_16x16x32_bf16 v[54:57], v[168:171], v[208:211], v[54:57]
	v_mfma_f32_16x16x32_bf16 v[54:57], v[146:149], v[204:207], v[54:57]
	v_mfma_f32_16x16x32_bf16 v[38:41], v[146:149], v[212:215], v[38:41]
	v_mfma_f32_16x16x32_bf16 v[38:41], v[168:171], v[216:219], v[38:41]
	v_mfma_f32_16x16x32_bf16 v[30:33], v[176:179], v[216:219], v[30:33]
	v_mfma_f32_16x16x32_bf16 v[30:33], v[172:175], v[212:215], v[30:33]
	v_mfma_f32_16x16x32_bf16 v[14:17], v[172:175], v[220:223], v[14:17]
	v_mfma_f32_16x16x32_bf16 v[14:17], v[176:179], v[224:227], v[14:17]
	v_mfma_f32_16x16x32_bf16 v[22:25], v[168:171], v[224:227], v[22:25]
	v_mfma_f32_16x16x32_bf16 v[22:25], v[146:149], v[220:223], v[22:25]
	v_mfma_f32_16x16x32_bf16 v[50:53], v[180:183], v[196:199], v[50:53]
	v_mfma_f32_16x16x32_bf16 v[50:53], v[184:187], v[200:203], v[50:53]
	v_mfma_f32_16x16x32_bf16 v[42:45], v[192:195], v[200:203], v[42:45]
	v_mfma_f32_16x16x32_bf16 v[42:45], v[188:191], v[196:199], v[42:45]
	v_mfma_f32_16x16x32_bf16 v[26:29], v[188:191], v[204:207], v[26:29]
	v_mfma_f32_16x16x32_bf16 v[26:29], v[192:195], v[208:211], v[26:29]
	v_mfma_f32_16x16x32_bf16 v[34:37], v[184:187], v[208:211], v[34:37]
	v_mfma_f32_16x16x32_bf16 v[34:37], v[180:183], v[204:207], v[34:37]
	v_mfma_f32_16x16x32_bf16 v[18:21], v[180:183], v[212:215], v[18:21]
	v_mfma_f32_16x16x32_bf16 v[18:21], v[184:187], v[216:219], v[18:21]
	v_mfma_f32_16x16x32_bf16 v[10:13], v[192:195], v[216:219], v[10:13]
	v_mfma_f32_16x16x32_bf16 v[10:13], v[188:191], v[212:215], v[10:13]
	v_mfma_f32_16x16x32_bf16 v[2:5], v[188:191], v[220:223], v[2:5]
	v_mfma_f32_16x16x32_bf16 v[2:5], v[192:195], v[224:227], v[2:5]
	s_setprio 2
	s_barrier
; #define PG8_STAGE(bufoff, gbase, voff) do { _Pragma("unroll") for (int _i = 0; _i < 2; ++_i) \
;         __builtin_amdgcn_global_load_lds((const unsigned*)((const char*)(gbase) + (voff)[_i]), (PG8_LAS unsigned*)(lds + (bufoff) + ldsw + _i * 8192), 16, 0, 0); } while (0)
; #define PG8_LDA(dst, b, h) do { _Pragma("unroll") for (int m = 0; m < 4; ++m) _Pragma("unroll") for (int k = 0; k < 2; ++k) dst[m][k] = *(const PG8_LAS bf16x8*)(lds + PG8_SA(b, h) + aoff + m * 2048 + k * 1024); } while (0)
; #define PG8_LDB(dst, b, h) do { _Pragma("unroll") for (int n = 0; n < 2; ++n) _Pragma("unroll") for (int k = 0; k < 2; ++k) dst[n][k] = *(const PG8_LAS bf16x8*)(lds + PG8_SB(b, h) + boff + n * 2048 + k * 1024); } while (0)
; #define PG8_MMA(ai, bj, At, Bt) do { __builtin_amdgcn_s_setprio(1); _Pragma("unroll") for (int m = 0; m < 4; ++m) _Pragma("unroll") for (int n = 0; n < 2; ++n) _Pragma("unroll") for (int k = 0; k < 2; ++k) \
;         acc[ai][bj][m][n] = __builtin_amdgcn_mfma_f32_16x16x32_bf16(Bt[n][k], At[m][k], acc[ai][bj][m][n], 0, 0, 0); __builtin_amdgcn_s_setprio(0); } while (0)
; template <class Epi, class Sched, bool ALIGN_EPI = false, bool SP2 = false>
; __device__ __forceinline__ void gemm_phase(PG8_LAS unsigned char* lds, const Gemm g, const Sched& S, const Epi& E) {
;     ...
;             if constexpr (SP2) {
;             PG8_LDB(B0, 0, 0); PG8_LDB(B1, 0, 1); PG8_SCHED; PG8_LDA(At, 0, 0); PG8_STAGE(PG8_SA(1, 1), a1 + hstepA, voffA);
;             PG8_WAIT_V(8); PG8_WAIT_L(0); PG8_BAR; PG8_MMA(0, 0, At, B0); PG8_MMA(0, 1, At, B1); PG8_BAR; PG8_SCHED;
;             PG8_LDA(At, 0, 1); PG8_STAGE(PG8_SB(0, 0), b2, voffB); PG8_STAGE(PG8_SB(0, 1), b2 + hstepB, voffB); PG8_STAGE(PG8_SA(0, 0), a2, voffA);
;             PG8_WAIT_V(8); PG8_WAIT_L(0); PG8_BAR; PG8_MMA(1, 0, At, B0); PG8_MMA(1, 1, At, B1); PG8_BAR; PG8_SCHED;
;             PG8_LDB(B0, 1, 0); PG8_LDB(B1, 1, 1); PG8_SCHED; PG8_LDA(At, 1, 0); PG8_STAGE(PG8_SA(0, 1), a2 + hstepA, voffA);
;             PG8_WAIT_V(8); PG8_WAIT_L(0); PG8_BAR; PG8_MMA(0, 0, At, B0); PG8_MMA(0, 1, At, B1); PG8_BAR; PG8_SCHED;
;             PG8_LDA(At, 1, 1); PG8_STAGE(PG8_SB(1, 0), b3, voffB); PG8_STAGE(PG8_SB(1, 1), b3 + hstepB, voffB); PG8_STAGE(PG8_SA(1, 0), a3, voffA);
;             PG8_WAIT_V(8); PG8_WAIT_L(0); PG8_BAR; PG8_MMA(1, 0, At, B0); PG8_MMA(1, 1, At, B1); PG8_BAR; PG8_SCHED;
	v_mfma_f32_16x16x32_bf16 v[6:9], v[184:187], v[224:227], v[6:9]
	v_mfma_f32_16x16x32_bf16 v[6:9], v[180:183], v[220:223], v[6:9]
	s_setprio 0
	s_add_i32 s61, 0, 0x18000
	v_add_u32_e32 v150, s61, v158
	s_add_i32 s62, 0, 0x1c000
	ds_read_b128 v[146:149], v150
	ds_read_b128 v[168:171], v150 offset:1024
	ds_read_b128 v[172:175], v150 offset:2048
	ds_read_b128 v[176:179], v150 offset:3072
	v_add_u32_e32 v150, s62, v158
	ds_read_b128 v[180:183], v150
	ds_read_b128 v[184:187], v150 offset:1024
	ds_read_b128 v[188:191], v150 offset:2048
	ds_read_b128 v[192:195], v150 offset:3072
	s_add_u32 s26, s26, 0x100000
	s_addc_u32 s27, s27, 0
	s_mov_b32 m0, s31
	ds_read_b128 v[196:199], v162 offset:32768
	ds_read_b128 v[200:203], v162 offset:33792
	ds_read_b128 v[204:207], v162 offset:34816
	ds_read_b128 v[208:211], v162 offset:35840
	ds_read_b128 v[212:215], v162 offset:36864
	ds_read_b128 v[216:219], v162 offset:37888
	ds_read_b128 v[220:223], v162 offset:38912
	ds_read_b128 v[224:227], v162 offset:39936
	global_load_lds_dwordx4 v130, s[26:27]
	s_mov_b32 m0, s33
	s_nop 0
	global_load_lds_dwordx4 v132, s[26:27]
	s_waitcnt vmcnt(8)
	s_waitcnt lgkmcnt(0)
	s_barrier
	s_setprio 1
	s_waitcnt lgkmcnt(0)
	v_mfma_f32_16x16x32_bf16 v[126:129], v[146:149], v[196:199], v[126:129]
	v_mfma_f32_16x16x32_bf16 v[126:129], v[168:171], v[200:203], v[126:129]
	v_mfma_f32_16x16x32_bf16 v[122:125], v[176:179], v[200:203], v[122:125]
	v_mfma_f32_16x16x32_bf16 v[122:125], v[172:175], v[196:199], v[122:125]
	v_mfma_f32_16x16x32_bf16 v[114:117], v[172:175], v[204:207], v[114:117]
	v_mfma_f32_16x16x32_bf16 v[114:117], v[176:179], v[208:211], v[114:117]
	v_mfma_f32_16x16x32_bf16 v[118:121], v[168:171], v[208:211], v[118:121]
	v_mfma_f32_16x16x32_bf16 v[118:121], v[146:149], v[204:207], v[118:121]
	v_mfma_f32_16x16x32_bf16 v[110:113], v[146:149], v[212:215], v[110:113]
	v_mfma_f32_16x16x32_bf16 v[110:113], v[168:171], v[216:219], v[110:113]
	v_mfma_f32_16x16x32_bf16 v[98:101], v[176:179], v[216:219], v[98:101]
	v_mfma_f32_16x16x32_bf16 v[98:101], v[172:175], v[212:215], v[98:101]
	v_mfma_f32_16x16x32_bf16 v[78:81], v[172:175], v[220:223], v[78:81]
	v_mfma_f32_16x16x32_bf16 v[78:81], v[176:179], v[224:227], v[78:81]
	v_mfma_f32_16x16x32_bf16 v[82:85], v[168:171], v[224:227], v[82:85]
	v_mfma_f32_16x16x32_bf16 v[82:85], v[146:149], v[220:223], v[82:85]
	v_mfma_f32_16x16x32_bf16 v[106:109], v[180:183], v[196:199], v[106:109]
	v_mfma_f32_16x16x32_bf16 v[106:109], v[184:187], v[200:203], v[106:109]
	v_mfma_f32_16x16x32_bf16 v[102:105], v[192:195], v[200:203], v[102:105]
	v_mfma_f32_16x16x32_bf16 v[102:105], v[188:191], v[196:199], v[102:105]
	v_mfma_f32_16x16x32_bf16 v[90:93], v[188:191], v[204:207], v[90:93]
	v_mfma_f32_16x16x32_bf16 v[90:93], v[192:195], v[208:211], v[90:93]
	v_mfma_f32_16x16x32_bf16 v[94:97], v[184:187], v[208:211], v[94:97]
	v_mfma_f32_16x16x32_bf16 v[94:97], v[180:183], v[204:207], v[94:97]
	v_mfma_f32_16x16x32_bf16 v[86:89], v[180:183], v[212:215], v[86:89]
	v_mfma_f32_16x16x32_bf16 v[86:89], v[184:187], v[216:219], v[86:89]
	v_mfma_f32_16x16x32_bf16 v[74:77], v[192:195], v[216:219], v[74:77]
	v_mfma_f32_16x16x32_bf16 v[74:77], v[188:191], v[212:215], v[74:77]
	v_mfma_f32_16x16x32_bf16 v[66:69], v[188:191], v[220:223], v[66:69]
	v_mfma_f32_16x16x32_bf16 v[66:69], v[192:195], v[224:227], v[66:69]
	s_setprio 2
	s_barrier
	v_mfma_f32_16x16x32_bf16 v[70:73], v[184:187], v[224:227], v[70:73]
	v_mfma_f32_16x16x32_bf16 v[70:73], v[180:183], v[220:223], v[70:73]
	s_setprio 0
	s_add_i32 s26, s61, s3
	s_mov_b32 m0, s26
	ds_read_b128 v[196:199], v162 offset:49152
	ds_read_b128 v[200:203], v162 offset:50176
	ds_read_b128 v[204:207], v162 offset:51200
	ds_read_b128 v[208:211], v162 offset:52224
	ds_read_b128 v[212:215], v162 offset:53248
	ds_read_b128 v[216:219], v162 offset:54272
	ds_read_b128 v[220:223], v162 offset:55296
	ds_read_b128 v[224:227], v162 offset:56320
	global_load_lds_dwordx4 v136, s[98:99]
	s_add_i32 m0, s26, 0x2000
	s_add_u32 s24, s24, 0x100080
	s_addc_u32 s25, s25, 0
	s_add_i32 s26, s62, s3
	global_load_lds_dwordx4 v134, s[98:99]
	s_mov_b32 m0, s26
	s_nop 0
	global_load_lds_dwordx4 v136, s[24:25]
	s_add_i32 m0, s26, 0x2000
	s_nop 0
	global_load_lds_dwordx4 v134, s[24:25]
	s_mov_b32 m0, s35
	s_nop 0
	global_load_lds_dwordx4 v130, s[100:101]
	s_mov_b32 m0, s36
	s_nop 0
	global_load_lds_dwordx4 v132, s[100:101]
	s_waitcnt vmcnt(8)
	s_waitcnt lgkmcnt(0)
	s_barrier
	s_setprio 1
	s_waitcnt lgkmcnt(0)
	v_mfma_f32_16x16x32_bf16 v[62:65], v[146:149], v[196:199], v[62:65]
	v_mfma_f32_16x16x32_bf16 v[62:65], v[168:171], v[200:203], v[62:65]
	v_mfma_f32_16x16x32_bf16 v[58:61], v[176:179], v[200:203], v[58:61]
	v_mfma_f32_16x16x32_bf16 v[58:61], v[172:175], v[196:199], v[58:61]
	v_mfma_f32_16x16x32_bf16 v[46:49], v[172:175], v[204:207], v[46:49]
	v_mfma_f32_16x16x32_bf16 v[46:49], v[176:179], v[208:211], v[46:49]
	v_mfma_f32_16x16x32_bf16 v[54:57], v[168:171], v[208:211], v[54:57]
	v_mfma_f32_16x16x32_bf16 v[54:57], v[146:149], v[204:207], v[54:57]
	v_mfma_f32_16x16x32_bf16 v[38:41], v[146:149], v[212:215], v[38:41]
	v_mfma_f32_16x16x32_bf16 v[38:41], v[168:171], v[216:219], v[38:41]
	v_mfma_f32_16x16x32_bf16 v[30:33], v[176:179], v[216:219], v[30:33]
	v_mfma_f32_16x16x32_bf16 v[30:33], v[172:175], v[212:215], v[30:33]
	v_mfma_f32_16x16x32_bf16 v[14:17], v[172:175], v[220:223], v[14:17]
	v_mfma_f32_16x16x32_bf16 v[14:17], v[176:179], v[224:227], v[14:17]
	v_mfma_f32_16x16x32_bf16 v[22:25], v[168:171], v[224:227], v[22:25]
	v_mfma_f32_16x16x32_bf16 v[22:25], v[146:149], v[220:223], v[22:25]
	v_mfma_f32_16x16x32_bf16 v[50:53], v[180:183], v[196:199], v[50:53]
	v_mfma_f32_16x16x32_bf16 v[50:53], v[184:187], v[200:203], v[50:53]
	v_mfma_f32_16x16x32_bf16 v[42:45], v[192:195], v[200:203], v[42:45]
	v_mfma_f32_16x16x32_bf16 v[42:45], v[188:191], v[196:199], v[42:45]
	v_mfma_f32_16x16x32_bf16 v[26:29], v[188:191], v[204:207], v[26:29]
	v_mfma_f32_16x16x32_bf16 v[26:29], v[192:195], v[208:211], v[26:29]
	v_mfma_f32_16x16x32_bf16 v[34:37], v[184:187], v[208:211], v[34:37]
	v_mfma_f32_16x16x32_bf16 v[34:37], v[180:183], v[204:207], v[34:37]
	v_mfma_f32_16x16x32_bf16 v[18:21], v[180:183], v[212:215], v[18:21]
	v_mfma_f32_16x16x32_bf16 v[18:21], v[184:187], v[216:219], v[18:21]
	v_mfma_f32_16x16x32_bf16 v[10:13], v[192:195], v[216:219], v[10:13]
	v_mfma_f32_16x16x32_bf16 v[10:13], v[188:191], v[212:215], v[10:13]
	v_mfma_f32_16x16x32_bf16 v[2:5], v[188:191], v[220:223], v[2:5]
	v_mfma_f32_16x16x32_bf16 v[2:5], v[192:195], v[224:227], v[2:5]
	s_setprio 2
	s_barrier
	v_mfma_f32_16x16x32_bf16 v[6:9], v[184:187], v[224:227], v[6:9]
	v_mfma_f32_16x16x32_bf16 v[6:9], v[180:183], v[220:223], v[6:9]
	s_setprio 0
	s_add_i32 s60, s60, 2
	s_add_u32 s22, s22, 0x100
	s_addc_u32 s23, s23, 0
	s_add_u32 s52, s52, 0x100
	s_addc_u32 s53, s53, 0
	s_cmp_gt_u32 s60, 61
	s_cbranch_scc0 .LBB0_525
	s_and_b64 vcc, exec, s[10:11]
	s_cbranch_vccz .LBB0_528
	s_barrier

; #define PG8_STAGE(bufoff, gbase, voff) do { _Pragma("unroll") for (int _i = 0; _i < 2; ++_i) \
;         __builtin_amdgcn_global_load_lds((const unsigned*)((const char*)(gbase) + (voff)[_i]), (PG8_LAS unsigned*)(lds + (bufoff) + ldsw + _i * 8192), 16, 0, 0); } while (0)
; #define PG8_LDA(dst, b, h) do { _Pragma("unroll") for (int m = 0; m < 4; ++m) _Pragma("unroll") for (int k = 0; k < 2; ++k) dst[m][k] = *(const PG8_LAS bf16x8*)(lds + PG8_SA(b, h) + aoff + m * 2048 + k * 1024); } while (0)
; #define PG8_BAR __builtin_amdgcn_s_barrier()
; template <class Epi, class Sched, bool ALIGN_EPI = false, bool SP2 = false>
; __device__ __forceinline__ void gemm_phase(PG8_LAS unsigned char* lds, const Gemm g, const Sched& S, const Epi& E) {
;     ...
;         for (int t = 0; t < nt; t += 2) {
;             const bool last = (t == nt - 2);
;             const char* a1 = cA + (size_t)(t + 1) * kstep + (t >= g.kj_t ? g.kj_bytes : 0);
;             const char* a2 = last ? nA : cA + (size_t)(t + 2) * kstep + (t + 2 >= g.kj_t ? g.kj_bytes : 0); const char* b2 = last ? nB : cB + (size_t)(t + 2) * kstep;
;             const char* a3 = a2 + kstep; const char* b3 = b2 + kstep;
;             if (last && has_next) S.a_ready(nxt);
;             if constexpr (Epi::MIDK) { if (t == g.kj_t) E.midk(acc, cur, wr, fr); }
;             if constexpr (SP2) {
;             PG8_LDB(B0, 0, 0); PG8_LDB(B1, 0, 1); PG8_SCHED; PG8_LDA(At, 0, 0); PG8_STAGE(PG8_SA(1, 1), a1 + hstepA, voffA);
;             PG8_WAIT_V(8); PG8_WAIT_L(0); PG8_BAR; PG8_MMA(0, 0, At, B0); PG8_MMA(0, 1, At, B1); PG8_BAR; PG8_SCHED;
;             PG8_LDA(At, 0, 1); PG8_STAGE(PG8_SB(0, 0), b2, voffB); PG8_STAGE(PG8_SB(0, 1), b2 + hstepB, voffB); PG8_STAGE(PG8_SA(0, 0), a2, voffA);
;             PG8_WAIT_V(8); PG8_WAIT_L(0); PG8_BAR; PG8_MMA(1, 0, At, B0); PG8_MMA(1, 1, At, B1); PG8_BAR; PG8_SCHED;
;             PG8_LDB(B0, 1, 0); PG8_LDB(B1, 1, 1); PG8_SCHED; PG8_LDA(At, 1, 0); PG8_STAGE(PG8_SA(0, 1), a2 + hstepA, voffA);
;             PG8_WAIT_V(8); PG8_WAIT_L(0); PG8_BAR; PG8_MMA(0, 0, At, B0); PG8_MMA(0, 1, At, B1); PG8_BAR; PG8_SCHED;
;             PG8_LDA(At, 1, 1); PG8_STAGE(PG8_SB(1, 0), b3, voffB); PG8_STAGE(PG8_SB(1, 1), b3 + hstepB, voffB); PG8_STAGE(PG8_SA(1, 0), a3, voffA);
;             PG8_WAIT_V(8); PG8_WAIT_L(0); PG8_BAR; PG8_MMA(1, 0, At, B0); PG8_MMA(1, 1, At, B1); PG8_BAR; PG8_SCHED;
.LBB0_882:
	ds_read_b128 v[128:131], v192
	ds_read_b128 v[132:135], v192 offset:1024
	ds_read_b128 v[136:139], v192 offset:2048
	ds_read_b128 v[140:143], v192 offset:3072
	ds_read_b128 v[160:163], v193
	ds_read_b128 v[168:171], v193 offset:1024
	ds_read_b128 v[172:175], v193 offset:2048
	ds_read_b128 v[176:179], v193 offset:3072
	s_add_u32 s36, s6, 0xffb70080
	s_addc_u32 s37, s7, -1
	s_cmpk_eq_i32 s65, 0x7c
	s_cselect_b32 s39, s29, s37
	s_cselect_b32 s38, s28, s36
	s_cselect_b32 s37, s27, s64
	s_cselect_b32 s36, s35, s63
	s_add_u32 s98, s36, 0x80
	s_addc_u32 s99, s37, 0
	s_add_u32 s100, s38, 0x80
	s_addc_u32 s101, s39, 0
	s_add_i32 m0, s41, 0xc000
	ds_read_b128 v[180:183], v194
	ds_read_b128 v[184:187], v194 offset:1024
	ds_read_b128 v[196:199], v194 offset:2048
	ds_read_b128 v[200:203], v194 offset:3072
	ds_read_b128 v[204:207], v194 offset:4096
	ds_read_b128 v[208:211], v194 offset:5120
	ds_read_b128 v[212:215], v194 offset:6144
	ds_read_b128 v[216:219], v194 offset:7168
	global_load_lds_dwordx4 v152, s[6:7]
	s_add_i32 m0, s41, 0xe000
	s_nop 0
	global_load_lds_dwordx4 v154, s[6:7]
	s_waitcnt vmcnt(8)
	s_waitcnt lgkmcnt(0)
	s_barrier
	s_setprio 1
	s_waitcnt lgkmcnt(0)
	v_mfma_f32_16x16x32_bf16 v[124:127], v[128:131], v[180:183], v[124:127]
	v_mfma_f32_16x16x32_bf16 v[124:127], v[132:135], v[184:187], v[124:127]
	v_mfma_f32_16x16x32_bf16 v[120:123], v[140:143], v[184:187], v[120:123]
	v_mfma_f32_16x16x32_bf16 v[120:123], v[136:139], v[180:183], v[120:123]
	v_mfma_f32_16x16x32_bf16 v[104:107], v[136:139], v[196:199], v[104:107]
	v_mfma_f32_16x16x32_bf16 v[104:107], v[140:143], v[200:203], v[104:107]
	v_mfma_f32_16x16x32_bf16 v[108:111], v[132:135], v[200:203], v[108:111]
	v_mfma_f32_16x16x32_bf16 v[108:111], v[128:131], v[196:199], v[108:111]
	v_mfma_f32_16x16x32_bf16 v[92:95], v[128:131], v[204:207], v[92:95]
	v_mfma_f32_16x16x32_bf16 v[92:95], v[132:135], v[208:211], v[92:95]
	v_mfma_f32_16x16x32_bf16 v[88:91], v[140:143], v[208:211], v[88:91]
	v_mfma_f32_16x16x32_bf16 v[88:91], v[136:139], v[204:207], v[88:91]
	v_mfma_f32_16x16x32_bf16 v[72:75], v[136:139], v[212:215], v[72:75]
	v_mfma_f32_16x16x32_bf16 v[72:75], v[140:143], v[216:219], v[72:75]
	v_mfma_f32_16x16x32_bf16 v[76:79], v[132:135], v[216:219], v[76:79]
	v_mfma_f32_16x16x32_bf16 v[76:79], v[128:131], v[212:215], v[76:79]
	v_mfma_f32_16x16x32_bf16 v[116:119], v[160:163], v[180:183], v[116:119]
	v_mfma_f32_16x16x32_bf16 v[116:119], v[168:171], v[184:187], v[116:119]
	v_mfma_f32_16x16x32_bf16 v[112:115], v[176:179], v[184:187], v[112:115]
	v_mfma_f32_16x16x32_bf16 v[112:115], v[172:175], v[180:183], v[112:115]
	v_mfma_f32_16x16x32_bf16 v[96:99], v[172:175], v[196:199], v[96:99]
	v_mfma_f32_16x16x32_bf16 v[96:99], v[176:179], v[200:203], v[96:99]
	v_mfma_f32_16x16x32_bf16 v[100:103], v[168:171], v[200:203], v[100:103]
	v_mfma_f32_16x16x32_bf16 v[100:103], v[160:163], v[196:199], v[100:103]
	v_mfma_f32_16x16x32_bf16 v[84:87], v[160:163], v[204:207], v[84:87]
	v_mfma_f32_16x16x32_bf16 v[84:87], v[168:171], v[208:211], v[84:87]
	v_mfma_f32_16x16x32_bf16 v[80:83], v[176:179], v[208:211], v[80:83]
	v_mfma_f32_16x16x32_bf16 v[80:83], v[172:175], v[204:207], v[80:83]
	v_mfma_f32_16x16x32_bf16 v[64:67], v[172:175], v[212:215], v[64:67]
	v_mfma_f32_16x16x32_bf16 v[64:67], v[176:179], v[216:219], v[64:67]
	s_setprio 2
	s_barrier
	v_mfma_f32_16x16x32_bf16 v[68:71], v[168:171], v[216:219], v[68:71]
	v_mfma_f32_16x16x32_bf16 v[68:71], v[160:163], v[212:215], v[68:71]
	s_setprio 0
	s_add_i32 s66, s52, s40
	s_mov_b32 m0, s66
	ds_read_b128 v[180:183], v194 offset:16384
	ds_read_b128 v[184:187], v194 offset:17408
	ds_read_b128 v[196:199], v194 offset:18432
	ds_read_b128 v[200:203], v194 offset:19456
	ds_read_b128 v[204:207], v194 offset:20480
	ds_read_b128 v[208:211], v194 offset:21504
	ds_read_b128 v[212:215], v194 offset:22528
	ds_read_b128 v[216:219], v194 offset:23552
	global_load_lds_dwordx4 v146, s[36:37]
	s_add_i32 m0, s66, 0x2000
	s_add_u32 s66, s36, 0x200000
	s_addc_u32 s67, s37, 0
	s_add_i32 s68, s53, s40
	global_load_lds_dwordx4 v150, s[36:37]
	s_mov_b32 m0, s68
	s_nop 0
	global_load_lds_dwordx4 v146, s[66:67]
	s_add_i32 m0, s68, 0x2000
	s_nop 0
	global_load_lds_dwordx4 v150, s[66:67]
	s_mov_b32 m0, s41
	s_nop 0
	global_load_lds_dwordx4 v144, s[38:39]
	s_mov_b32 m0, s44
	s_nop 0
	global_load_lds_dwordx4 v148, s[38:39]
	s_waitcnt vmcnt(8)
	s_waitcnt lgkmcnt(0)
	s_barrier
	s_setprio 1
	s_waitcnt lgkmcnt(0)
	v_mfma_f32_16x16x32_bf16 v[60:63], v[128:131], v[180:183], v[60:63]
	v_mfma_f32_16x16x32_bf16 v[60:63], v[132:135], v[184:187], v[60:63]
	v_mfma_f32_16x16x32_bf16 v[56:59], v[140:143], v[184:187], v[56:59]
	v_mfma_f32_16x16x32_bf16 v[56:59], v[136:139], v[180:183], v[56:59]
	v_mfma_f32_16x16x32_bf16 v[40:43], v[136:139], v[196:199], v[40:43]
	v_mfma_f32_16x16x32_bf16 v[40:43], v[140:143], v[200:203], v[40:43]
	v_mfma_f32_16x16x32_bf16 v[44:47], v[132:135], v[200:203], v[44:47]
	v_mfma_f32_16x16x32_bf16 v[44:47], v[128:131], v[196:199], v[44:47]
	v_mfma_f32_16x16x32_bf16 v[28:31], v[128:131], v[204:207], v[28:31]
	v_mfma_f32_16x16x32_bf16 v[28:31], v[132:135], v[208:211], v[28:31]
	v_mfma_f32_16x16x32_bf16 v[24:27], v[140:143], v[208:211], v[24:27]
	v_mfma_f32_16x16x32_bf16 v[24:27], v[136:139], v[204:207], v[24:27]
	v_mfma_f32_16x16x32_bf16 v[8:11], v[136:139], v[212:215], v[8:11]
	v_mfma_f32_16x16x32_bf16 v[8:11], v[140:143], v[216:219], v[8:11]
	v_mfma_f32_16x16x32_bf16 v[12:15], v[132:135], v[216:219], v[12:15]
	v_mfma_f32_16x16x32_bf16 v[12:15], v[128:131], v[212:215], v[12:15]
	v_mfma_f32_16x16x32_bf16 v[52:55], v[160:163], v[180:183], v[52:55]
	v_mfma_f32_16x16x32_bf16 v[52:55], v[168:171], v[184:187], v[52:55]
	v_mfma_f32_16x16x32_bf16 v[48:51], v[176:179], v[184:187], v[48:51]
	v_mfma_f32_16x16x32_bf16 v[48:51], v[172:175], v[180:183], v[48:51]
	v_mfma_f32_16x16x32_bf16 v[32:35], v[172:175], v[196:199], v[32:35]
	v_mfma_f32_16x16x32_bf16 v[32:35], v[176:179], v[200:203], v[32:35]
	v_mfma_f32_16x16x32_bf16 v[36:39], v[168:171], v[200:203], v[36:39]
	v_mfma_f32_16x16x32_bf16 v[36:39], v[160:163], v[196:199], v[36:39]
	v_mfma_f32_16x16x32_bf16 v[20:23], v[160:163], v[204:207], v[20:23]
	v_mfma_f32_16x16x32_bf16 v[20:23], v[168:171], v[208:211], v[20:23]
	v_mfma_f32_16x16x32_bf16 v[16:19], v[176:179], v[208:211], v[16:19]
	v_mfma_f32_16x16x32_bf16 v[16:19], v[172:175], v[204:207], v[16:19]
	v_mfma_f32_16x16x32_bf16 v[0:3], v[172:175], v[212:215], v[0:3]
	v_mfma_f32_16x16x32_bf16 v[0:3], v[176:179], v[216:219], v[0:3]
	s_setprio 2
	s_barrier
; #define PG8_STAGE(bufoff, gbase, voff) do { _Pragma("unroll") for (int _i = 0; _i < 2; ++_i) \
;         __builtin_amdgcn_global_load_lds((const unsigned*)((const char*)(gbase) + (voff)[_i]), (PG8_LAS unsigned*)(lds + (bufoff) + ldsw + _i * 8192), 16, 0, 0); } while (0)
; #define PG8_LDA(dst, b, h) do { _Pragma("unroll") for (int m = 0; m < 4; ++m) _Pragma("unroll") for (int k = 0; k < 2; ++k) dst[m][k] = *(const PG8_LAS bf16x8*)(lds + PG8_SA(b, h) + aoff + m * 2048 + k * 1024); } while (0)
; #define PG8_LDB(dst, b, h) do { _Pragma("unroll") for (int n = 0; n < 2; ++n) _Pragma("unroll") for (int k = 0; k < 2; ++k) dst[n][k] = *(const PG8_LAS bf16x8*)(lds + PG8_SB(b, h) + boff + n * 2048 + k * 1024); } while (0)
; #define PG8_MMA(ai, bj, At, Bt) do { __builtin_amdgcn_s_setprio(1); _Pragma("unroll") for (int m = 0; m < 4; ++m) _Pragma("unroll") for (int n = 0; n < 2; ++n) _Pragma("unroll") for (int k = 0; k < 2; ++k) \
;         acc[ai][bj][m][n] = __builtin_amdgcn_mfma_f32_16x16x32_bf16(Bt[n][k], At[m][k], acc[ai][bj][m][n], 0, 0, 0); __builtin_amdgcn_s_setprio(0); } while (0)
; template <class Epi, class Sched, bool ALIGN_EPI = false, bool SP2 = false>
; __device__ __forceinline__ void gemm_phase(PG8_LAS unsigned char* lds, const Gemm g, const Sched& S, const Epi& E) {
;     ...
;             if constexpr (SP2) {
;             PG8_LDB(B0, 0, 0); PG8_LDB(B1, 0, 1); PG8_SCHED; PG8_LDA(At, 0, 0); PG8_STAGE(PG8_SA(1, 1), a1 + hstepA, voffA);
;             PG8_WAIT_V(8); PG8_WAIT_L(0); PG8_BAR; PG8_MMA(0, 0, At, B0); PG8_MMA(0, 1, At, B1); PG8_BAR; PG8_SCHED;
;             PG8_LDA(At, 0, 1); PG8_STAGE(PG8_SB(0, 0), b2, voffB); PG8_STAGE(PG8_SB(0, 1), b2 + hstepB, voffB); PG8_STAGE(PG8_SA(0, 0), a2, voffA);
;             PG8_WAIT_V(8); PG8_WAIT_L(0); PG8_BAR; PG8_MMA(1, 0, At, B0); PG8_MMA(1, 1, At, B1); PG8_BAR; PG8_SCHED;
;             PG8_LDB(B0, 1, 0); PG8_LDB(B1, 1, 1); PG8_SCHED; PG8_LDA(At, 1, 0); PG8_STAGE(PG8_SA(0, 1), a2 + hstepA, voffA);
;             PG8_WAIT_V(8); PG8_WAIT_L(0); PG8_BAR; PG8_MMA(0, 0, At, B0); PG8_MMA(0, 1, At, B1); PG8_BAR; PG8_SCHED;
;             PG8_LDA(At, 1, 1); PG8_STAGE(PG8_SB(1, 0), b3, voffB); PG8_STAGE(PG8_SB(1, 1), b3 + hstepB, voffB); PG8_STAGE(PG8_SA(1, 0), a3, voffA);
;             PG8_WAIT_V(8); PG8_WAIT_L(0); PG8_BAR; PG8_MMA(1, 0, At, B0); PG8_MMA(1, 1, At, B1); PG8_BAR; PG8_SCHED;
	v_mfma_f32_16x16x32_bf16 v[4:7], v[168:171], v[216:219], v[4:7]
	v_mfma_f32_16x16x32_bf16 v[4:7], v[160:163], v[212:215], v[4:7]
	s_setprio 0
	s_add_i32 s66, 0, 0x18000
	s_add_i32 s67, 0, 0x1c000
	v_add_u32_e32 v140, s66, v190
	v_add_u32_e32 v176, s67, v190
	ds_read_b128 v[128:131], v140
	ds_read_b128 v[132:135], v140 offset:1024
	ds_read_b128 v[136:139], v140 offset:2048
	ds_read_b128 v[140:143], v140 offset:3072
	ds_read_b128 v[160:163], v176
	ds_read_b128 v[168:171], v176 offset:1024
	ds_read_b128 v[172:175], v176 offset:2048
	ds_read_b128 v[176:179], v176 offset:3072
	s_add_u32 s38, s38, 0x490000
	s_addc_u32 s39, s39, 0
	s_mov_b32 m0, s45
	ds_read_b128 v[180:183], v194 offset:32768
	ds_read_b128 v[184:187], v194 offset:33792
	ds_read_b128 v[196:199], v194 offset:34816
	ds_read_b128 v[200:203], v194 offset:35840
	ds_read_b128 v[204:207], v194 offset:36864
	ds_read_b128 v[208:211], v194 offset:37888
	ds_read_b128 v[212:215], v194 offset:38912
	ds_read_b128 v[216:219], v194 offset:39936
	global_load_lds_dwordx4 v144, s[38:39]
	s_mov_b32 m0, s46
	s_nop 0
	global_load_lds_dwordx4 v148, s[38:39]
	s_waitcnt vmcnt(8)
	s_waitcnt lgkmcnt(0)
	s_barrier
	s_setprio 1
	s_waitcnt lgkmcnt(0)
	v_mfma_f32_16x16x32_bf16 v[124:127], v[128:131], v[180:183], v[124:127]
	v_mfma_f32_16x16x32_bf16 v[124:127], v[132:135], v[184:187], v[124:127]
	v_mfma_f32_16x16x32_bf16 v[120:123], v[140:143], v[184:187], v[120:123]
	v_mfma_f32_16x16x32_bf16 v[120:123], v[136:139], v[180:183], v[120:123]
	v_mfma_f32_16x16x32_bf16 v[104:107], v[136:139], v[196:199], v[104:107]
	v_mfma_f32_16x16x32_bf16 v[104:107], v[140:143], v[200:203], v[104:107]
	v_mfma_f32_16x16x32_bf16 v[108:111], v[132:135], v[200:203], v[108:111]
	v_mfma_f32_16x16x32_bf16 v[108:111], v[128:131], v[196:199], v[108:111]
	v_mfma_f32_16x16x32_bf16 v[92:95], v[128:131], v[204:207], v[92:95]
	v_mfma_f32_16x16x32_bf16 v[92:95], v[132:135], v[208:211], v[92:95]
	v_mfma_f32_16x16x32_bf16 v[88:91], v[140:143], v[208:211], v[88:91]
	v_mfma_f32_16x16x32_bf16 v[88:91], v[136:139], v[204:207], v[88:91]
	v_mfma_f32_16x16x32_bf16 v[72:75], v[136:139], v[212:215], v[72:75]
	v_mfma_f32_16x16x32_bf16 v[72:75], v[140:143], v[216:219], v[72:75]
	v_mfma_f32_16x16x32_bf16 v[76:79], v[132:135], v[216:219], v[76:79]
	v_mfma_f32_16x16x32_bf16 v[76:79], v[128:131], v[212:215], v[76:79]
	v_mfma_f32_16x16x32_bf16 v[116:119], v[160:163], v[180:183], v[116:119]
	v_mfma_f32_16x16x32_bf16 v[116:119], v[168:171], v[184:187], v[116:119]
	v_mfma_f32_16x16x32_bf16 v[112:115], v[176:179], v[184:187], v[112:115]
	v_mfma_f32_16x16x32_bf16 v[112:115], v[172:175], v[180:183], v[112:115]
	v_mfma_f32_16x16x32_bf16 v[96:99], v[172:175], v[196:199], v[96:99]
	v_mfma_f32_16x16x32_bf16 v[96:99], v[176:179], v[200:203], v[96:99]
	v_mfma_f32_16x16x32_bf16 v[100:103], v[168:171], v[200:203], v[100:103]
	v_mfma_f32_16x16x32_bf16 v[100:103], v[160:163], v[196:199], v[100:103]
	v_mfma_f32_16x16x32_bf16 v[84:87], v[160:163], v[204:207], v[84:87]
	v_mfma_f32_16x16x32_bf16 v[84:87], v[168:171], v[208:211], v[84:87]
	v_mfma_f32_16x16x32_bf16 v[80:83], v[176:179], v[208:211], v[80:83]
	v_mfma_f32_16x16x32_bf16 v[80:83], v[172:175], v[204:207], v[80:83]
	v_mfma_f32_16x16x32_bf16 v[64:67], v[172:175], v[212:215], v[64:67]
	v_mfma_f32_16x16x32_bf16 v[64:67], v[176:179], v[216:219], v[64:67]
	s_setprio 2
	s_barrier
	v_mfma_f32_16x16x32_bf16 v[68:71], v[168:171], v[216:219], v[68:71]
	v_mfma_f32_16x16x32_bf16 v[68:71], v[160:163], v[212:215], v[68:71]
	s_setprio 0
	s_add_i32 s38, s66, s40
	s_mov_b32 m0, s38
	ds_read_b128 v[180:183], v194 offset:49152
	ds_read_b128 v[184:187], v194 offset:50176
	ds_read_b128 v[196:199], v194 offset:51200
	ds_read_b128 v[200:203], v194 offset:52224
	ds_read_b128 v[204:207], v194 offset:53248
	ds_read_b128 v[208:211], v194 offset:54272
	ds_read_b128 v[212:215], v194 offset:55296
	ds_read_b128 v[216:219], v194 offset:56320
	global_load_lds_dwordx4 v146, s[98:99]
	s_add_i32 m0, s38, 0x2000
	s_add_u32 s36, s36, 0x200080
	s_addc_u32 s37, s37, 0
	s_add_i32 s38, s67, s40
	global_load_lds_dwordx4 v150, s[98:99]
	s_mov_b32 m0, s38
	s_nop 0
	global_load_lds_dwordx4 v146, s[36:37]
	s_add_i32 m0, s38, 0x2000
	s_nop 0
	global_load_lds_dwordx4 v150, s[36:37]
	s_mov_b32 m0, s47
	s_nop 0
	global_load_lds_dwordx4 v144, s[100:101]
	s_mov_b32 m0, s48
	s_nop 0
	global_load_lds_dwordx4 v148, s[100:101]
	s_waitcnt vmcnt(8)
	s_waitcnt lgkmcnt(0)
	s_barrier
	s_setprio 1
	s_waitcnt lgkmcnt(0)
	v_mfma_f32_16x16x32_bf16 v[60:63], v[128:131], v[180:183], v[60:63]
	v_mfma_f32_16x16x32_bf16 v[60:63], v[132:135], v[184:187], v[60:63]
	v_mfma_f32_16x16x32_bf16 v[56:59], v[140:143], v[184:187], v[56:59]
	v_mfma_f32_16x16x32_bf16 v[56:59], v[136:139], v[180:183], v[56:59]
	v_mfma_f32_16x16x32_bf16 v[40:43], v[136:139], v[196:199], v[40:43]
	v_mfma_f32_16x16x32_bf16 v[40:43], v[140:143], v[200:203], v[40:43]
	v_mfma_f32_16x16x32_bf16 v[44:47], v[132:135], v[200:203], v[44:47]
	v_mfma_f32_16x16x32_bf16 v[44:47], v[128:131], v[196:199], v[44:47]
	v_mfma_f32_16x16x32_bf16 v[28:31], v[128:131], v[204:207], v[28:31]
	v_mfma_f32_16x16x32_bf16 v[28:31], v[132:135], v[208:211], v[28:31]
	v_mfma_f32_16x16x32_bf16 v[24:27], v[140:143], v[208:211], v[24:27]
	v_mfma_f32_16x16x32_bf16 v[24:27], v[136:139], v[204:207], v[24:27]
	v_mfma_f32_16x16x32_bf16 v[8:11], v[136:139], v[212:215], v[8:11]
	v_mfma_f32_16x16x32_bf16 v[8:11], v[140:143], v[216:219], v[8:11]
	v_mfma_f32_16x16x32_bf16 v[12:15], v[132:135], v[216:219], v[12:15]
	v_mfma_f32_16x16x32_bf16 v[12:15], v[128:131], v[212:215], v[12:15]
	v_mfma_f32_16x16x32_bf16 v[52:55], v[160:163], v[180:183], v[52:55]
	v_mfma_f32_16x16x32_bf16 v[52:55], v[168:171], v[184:187], v[52:55]
	v_mfma_f32_16x16x32_bf16 v[48:51], v[176:179], v[184:187], v[48:51]
	v_mfma_f32_16x16x32_bf16 v[48:51], v[172:175], v[180:183], v[48:51]
	v_mfma_f32_16x16x32_bf16 v[32:35], v[172:175], v[196:199], v[32:35]
	v_mfma_f32_16x16x32_bf16 v[32:35], v[176:179], v[200:203], v[32:35]
	v_mfma_f32_16x16x32_bf16 v[36:39], v[168:171], v[200:203], v[36:39]
	v_mfma_f32_16x16x32_bf16 v[36:39], v[160:163], v[196:199], v[36:39]
	v_mfma_f32_16x16x32_bf16 v[20:23], v[160:163], v[204:207], v[20:23]
	v_mfma_f32_16x16x32_bf16 v[20:23], v[168:171], v[208:211], v[20:23]
	v_mfma_f32_16x16x32_bf16 v[16:19], v[176:179], v[208:211], v[16:19]
	v_mfma_f32_16x16x32_bf16 v[16:19], v[172:175], v[204:207], v[16:19]
	v_mfma_f32_16x16x32_bf16 v[0:3], v[172:175], v[212:215], v[0:3]
	v_mfma_f32_16x16x32_bf16 v[0:3], v[176:179], v[216:219], v[0:3]
	s_setprio 2
	s_barrier
	v_mfma_f32_16x16x32_bf16 v[4:7], v[168:171], v[216:219], v[4:7]
	v_mfma_f32_16x16x32_bf16 v[4:7], v[160:163], v[212:215], v[4:7]
	s_setprio 0
	s_add_i32 s65, s65, 2
	s_add_u32 s6, s6, 0x100
	s_addc_u32 s7, s7, 0
	s_add_u32 s63, s63, 0x100
	s_addc_u32 s64, s64, 0
	s_cmpk_gt_u32 s65, 0x7d
	s_cbranch_scc0 .LBB0_882
	s_and_b64 vcc, exec, s[22:23]
	s_cbranch_vccz .LBB0_885
	s_barrier
